# bf16-residual GEMM epilogues (5 instances): single vmcnt(0) after the 16 residual loads replaced by graduated waits placed at first use of each load (counting younger stores), on top of pipelined out-
# speedup vs baseline: 1.0087x; 1.0087x over previous
; __device__ __forceinline__ unsigned cvt_pk_bf16(float lo, float hi) { unsigned r; asm volatile("v_cvt_pk_bf16_f32 %0, %1, %2" : "=v"(r) : "v"(lo), "v"(hi)); return r; }
;     __device__ __forceinline__ void operator()(const f32x4 (&acc)[2][2][4][2], const Unit& u, int wr, int wc, int fr, int fq) const {
;     ...
;             u32x4 bv[2][4][2];
; #pragma unroll
;             for (int ai = 0; ai < 2; ++ai)
; #pragma unroll
;                 for (int m = 0; m < 4; ++m)
; #pragma unroll
;                     for (int bj = 0; bj < 2; ++bj) bv[ai][m][bj] = *(const u32x4*)(baseb + (size_t)(row0 + ai * HALF + m * 16) * ldc + col0 + bj * HALF);
;             asm volatile("" ::: "memory");
; #pragma unroll
;             for (int ai = 0; ai < 2; ++ai)
; #pragma unroll
;                 for (int m = 0; m < 4; ++m)
; #pragma unroll
;                     for (int bj = 0; bj < 2; ++bj) { const u32x4 b = bv[ai][m][bj];
;                         const f32x4 v0 = acc[ai][bj][m][0] + (f32x4){__builtin_bit_cast(float, b.x << 16), __builtin_bit_cast(float, b.x & 0xffff0000u), __builtin_bit_cast(float, b.y << 16), __builtin_bit_cast(float, b.y & 0xffff0000u)};
;                         const f32x4 v1 = acc[ai][bj][m][1] + (f32x4){__builtin_bit_cast(float, b.z << 16), __builtin_bit_cast(float, b.z & 0xffff0000u), __builtin_bit_cast(float, b.w << 16), __builtin_bit_cast(float, b.w & 0xffff0000u)};
;                         u32x4 w; w.x = cvt_pk_bf16(v0[0], v0[1]); w.y = cvt_pk_bf16(v0[2], v0[3]); w.z = cvt_pk_bf16(v1[0], v1[1]); w.w = cvt_pk_bf16(v1[2], v1[3]);
;                         *(u32x4*)(outb + (size_t)(row0 + ai * HALF + m * 16) * ldc + col0 + bj * HALF) = w; }
.LBB0_455:
	v_lshl_or_b32 v130, s24, 8, v201
	v_lshl_add_u32 v128, s68, 8, v199
	v_ashrrev_i32_e32 v131, 31, v130
	v_lshlrev_b64 v[184:185], 1, v[130:131]
	v_ashrrev_i32_e32 v129, 31, v128
	v_lshl_add_u64 v[130:131], s[52:53], 0, v[184:185]
	v_lshlrev_b64 v[132:133], 12, v[128:129]
	v_lshl_add_u64 v[134:135], v[130:131], 0, v[132:133]
	global_load_dwordx4 v[206:209], v[134:135], off
	global_load_dwordx4 v[210:213], v[134:135], off offset:256
	v_or_b32_e32 v134, 16, v128
	v_ashrrev_i32_e32 v135, 31, v134
	v_lshlrev_b64 v[230:231], 12, v[134:135]
	v_lshl_add_u64 v[134:135], v[130:131], 0, v[230:231]
	global_load_dwordx4 v[214:217], v[134:135], off
	global_load_dwordx4 v[218:221], v[134:135], off offset:256
	v_or_b32_e32 v136, 32, v128
	v_or_b32_e32 v128, 48, v128
	s_mov_b64 s[24:25], 0x80000
	s_mov_b64 s[70:71], 0x90000
	v_ashrrev_i32_e32 v137, 31, v136
	v_ashrrev_i32_e32 v129, 31, v128
	v_lshlrev_b64 v[196:197], 12, v[136:137]
	v_lshlrev_b64 v[194:195], 12, v[128:129]
	v_lshl_add_u64 v[192:193], v[132:133], 0, s[24:25]
	v_lshl_add_u64 v[190:191], v[132:133], 0, s[70:71]
	v_lshl_add_u64 v[188:189], v[132:133], 0, s[44:45]
	v_lshl_add_u64 v[186:187], v[132:133], 0, s[48:49]
	v_lshl_add_u64 v[128:129], s[52:53], 0, v[132:133]
	v_lshl_add_u64 v[132:133], v[130:131], 0, v[196:197]
	v_lshl_add_u64 v[134:135], v[130:131], 0, v[194:195]
	v_lshl_add_u64 v[136:137], v[130:131], 0, v[192:193]
	v_lshl_add_u64 v[138:139], v[130:131], 0, v[190:191]
	v_lshl_add_u64 v[232:233], v[130:131], 0, v[188:189]
	v_lshl_add_u64 v[130:131], v[130:131], 0, v[186:187]
	v_lshl_add_u64 v[234:235], v[128:129], 0, v[184:185]
	global_load_dwordx4 v[222:225], v[132:133], off
	global_load_dwordx4 v[226:229], v[132:133], off offset:256
	global_load_dwordx4 v[164:167], v[134:135], off
	global_load_dwordx4 v[160:163], v[134:135], off offset:256
	global_load_dwordx4 v[156:159], v[136:137], off
	global_load_dwordx4 v[152:155], v[136:137], off offset:256
	global_load_dwordx4 v[148:151], v[138:139], off
	global_load_dwordx4 v[144:147], v[138:139], off offset:256
	global_load_dwordx4 v[140:143], v[232:233], off
	s_nop 0
	global_load_dwordx4 v[136:139], v[232:233], off offset:256
	global_load_dwordx4 v[132:135], v[130:131], off
	s_nop 0
	global_load_dwordx4 v[128:131], v[130:131], off offset:256
	s_andn2_b64 vcc, exec, s[4:5]
	s_mov_b64 s[4:5], -1
	s_waitcnt vmcnt(15)
	v_lshlrev_b32_e32 v232, 16, v206
	v_and_b32_e32 v233, 0xffff0000, v206
	v_lshlrev_b32_e32 v206, 16, v207
	v_and_b32_e32 v207, 0xffff0000, v207
	v_lshlrev_b32_e32 v236, 16, v208
	v_and_b32_e32 v237, 0xffff0000, v208
	v_lshlrev_b32_e32 v208, 16, v209
	v_and_b32_e32 v209, 0xffff0000, v209
	s_waitcnt vmcnt(14)
	v_lshlrev_b32_e32 v240, 16, v212
	v_and_b32_e32 v241, 0xffff0000, v212
	v_lshlrev_b32_e32 v212, 16, v213
	v_and_b32_e32 v213, 0xffff0000, v213
	v_lshlrev_b32_e32 v238, 16, v210
	v_and_b32_e32 v239, 0xffff0000, v210
	v_lshlrev_b32_e32 v210, 16, v211
	v_and_b32_e32 v211, 0xffff0000, v211
	v_pk_add_f32 v[126:127], v[126:127], v[206:207]
	v_pk_add_f32 v[124:125], v[124:125], v[232:233]
	v_pk_add_f32 v[122:123], v[122:123], v[208:209]
	v_pk_add_f32 v[120:121], v[120:121], v[236:237]
	v_pk_add_f32 v[206:207], v[106:107], v[212:213]
	v_pk_add_f32 v[208:209], v[104:105], v[240:241]
	v_cvt_pk_bf16_f32 v104, v124, v125
	v_cvt_pk_bf16_f32 v105, v126, v127
	v_cvt_pk_bf16_f32 v106, v120, v121
	v_cvt_pk_bf16_f32 v107, v122, v123
	s_waitcnt vmcnt(13)
	v_lshlrev_b32_e32 v244, 16, v216
	v_and_b32_e32 v245, 0xffff0000, v216
	v_pk_add_f32 v[114:115], v[114:115], v[210:211]
	v_pk_add_f32 v[112:113], v[112:113], v[238:239]
	global_store_dwordx4 v[234:235], v[104:107], off
	v_lshlrev_b32_e32 v242, 16, v214
	v_and_b32_e32 v243, 0xffff0000, v214
	v_cvt_pk_bf16_f32 v104, v112, v113
	v_cvt_pk_bf16_f32 v105, v114, v115
	v_cvt_pk_bf16_f32 v106, v208, v209
	v_cvt_pk_bf16_f32 v107, v206, v207
	v_lshlrev_b32_e32 v214, 16, v215
	v_and_b32_e32 v215, 0xffff0000, v215
	v_lshlrev_b32_e32 v216, 16, v217
	global_store_dwordx4 v[234:235], v[104:107], off offset:256
	v_and_b32_e32 v217, 0xffff0000, v217
	v_pk_add_f32 v[118:119], v[118:119], v[214:215]
	v_pk_add_f32 v[106:107], v[108:109], v[244:245]
	v_lshl_add_u64 v[108:109], s[52:53], 0, v[230:231]
	v_pk_add_f32 v[116:117], v[116:117], v[242:243]
	v_pk_add_f32 v[110:111], v[110:111], v[216:217]
	v_cvt_pk_bf16_f32 v104, v116, v117
	v_cvt_pk_bf16_f32 v105, v118, v119
	v_cvt_pk_bf16_f32 v106, v106, v107
	v_lshl_add_u64 v[108:109], v[108:109], 0, v[184:185]
	v_cvt_pk_bf16_f32 v107, v110, v111
	global_store_dwordx4 v[108:109], v[104:107], off
	s_nop 1
	s_waitcnt vmcnt(15)
	v_lshlrev_b32_e32 v104, 16, v218
	v_and_b32_e32 v105, 0xffff0000, v218
	v_lshlrev_b32_e32 v106, 16, v219
	v_and_b32_e32 v107, 0xffff0000, v219
	v_pk_add_f32 v[102:103], v[102:103], v[106:107]
	v_pk_add_f32 v[100:101], v[100:101], v[104:105]
	v_lshlrev_b32_e32 v104, 16, v220
	v_and_b32_e32 v105, 0xffff0000, v220
	v_lshlrev_b32_e32 v106, 16, v221
	v_and_b32_e32 v107, 0xffff0000, v221
	v_pk_add_f32 v[106:107], v[98:99], v[106:107]
	v_pk_add_f32 v[98:99], v[96:97], v[104:105]
	v_cvt_pk_bf16_f32 v96, v100, v101
	v_cvt_pk_bf16_f32 v97, v102, v103
	s_nop 0
	v_cvt_pk_bf16_f32 v98, v98, v99
	v_cvt_pk_bf16_f32 v99, v106, v107
	global_store_dwordx4 v[108:109], v[96:99], off offset:256
	s_nop 1
	s_waitcnt vmcnt(15)
; __device__ __forceinline__ unsigned cvt_pk_bf16(float lo, float hi) { unsigned r; asm volatile("v_cvt_pk_bf16_f32 %0, %1, %2" : "=v"(r) : "v"(lo), "v"(hi)); return r; }
;     __device__ __forceinline__ void operator()(const f32x4 (&acc)[2][2][4][2], const Unit& u, int wr, int wc, int fr, int fq) const {
;     ...
; #pragma unroll
;             for (int ai = 0; ai < 2; ++ai)
; #pragma unroll
;                 for (int m = 0; m < 4; ++m)
; #pragma unroll
;                     for (int bj = 0; bj < 2; ++bj) { const u32x4 b = bv[ai][m][bj];
;                         const f32x4 v0 = acc[ai][bj][m][0] + (f32x4){__builtin_bit_cast(float, b.x << 16), __builtin_bit_cast(float, b.x & 0xffff0000u), __builtin_bit_cast(float, b.y << 16), __builtin_bit_cast(float, b.y & 0xffff0000u)};
;                         const f32x4 v1 = acc[ai][bj][m][1] + (f32x4){__builtin_bit_cast(float, b.z << 16), __builtin_bit_cast(float, b.z & 0xffff0000u), __builtin_bit_cast(float, b.w << 16), __builtin_bit_cast(float, b.w & 0xffff0000u)};
;                         u32x4 w; w.x = cvt_pk_bf16(v0[0], v0[1]); w.y = cvt_pk_bf16(v0[2], v0[3]); w.z = cvt_pk_bf16(v1[0], v1[1]); w.w = cvt_pk_bf16(v1[2], v1[3]);
;                         *(u32x4*)(outb + (size_t)(row0 + ai * HALF + m * 16) * ldc + col0 + bj * HALF) = w; }
	v_lshlrev_b32_e32 v96, 16, v222
	v_and_b32_e32 v97, 0xffff0000, v222
	v_lshlrev_b32_e32 v98, 16, v223
	v_and_b32_e32 v99, 0xffff0000, v223
	v_pk_add_f32 v[94:95], v[94:95], v[98:99]
	v_pk_add_f32 v[92:93], v[92:93], v[96:97]
	v_lshlrev_b32_e32 v96, 16, v224
	v_and_b32_e32 v97, 0xffff0000, v224
	v_lshlrev_b32_e32 v98, 16, v225
	v_and_b32_e32 v99, 0xffff0000, v225
	v_pk_add_f32 v[98:99], v[90:91], v[98:99]
	v_pk_add_f32 v[90:91], v[88:89], v[96:97]
	v_cvt_pk_bf16_f32 v88, v92, v93
	v_lshl_add_u64 v[92:93], s[52:53], 0, v[196:197]
	v_cvt_pk_bf16_f32 v89, v94, v95
	v_cvt_pk_bf16_f32 v90, v90, v91
	v_cvt_pk_bf16_f32 v91, v98, v99
	v_lshl_add_u64 v[92:93], v[92:93], 0, v[184:185]
	global_store_dwordx4 v[92:93], v[88:91], off
	s_nop 1
	s_waitcnt vmcnt(15)
	v_lshlrev_b32_e32 v88, 16, v226
	v_and_b32_e32 v89, 0xffff0000, v226
	v_lshlrev_b32_e32 v90, 16, v227
	v_and_b32_e32 v91, 0xffff0000, v227
	v_pk_add_f32 v[86:87], v[86:87], v[90:91]
	v_pk_add_f32 v[84:85], v[84:85], v[88:89]
	v_lshlrev_b32_e32 v88, 16, v228
	v_and_b32_e32 v89, 0xffff0000, v228
	v_lshlrev_b32_e32 v90, 16, v229
	v_and_b32_e32 v91, 0xffff0000, v229
	v_pk_add_f32 v[90:91], v[82:83], v[90:91]
	v_pk_add_f32 v[82:83], v[80:81], v[88:89]
	v_cvt_pk_bf16_f32 v80, v84, v85
	v_cvt_pk_bf16_f32 v81, v86, v87
	s_nop 0
	v_cvt_pk_bf16_f32 v82, v82, v83
	v_cvt_pk_bf16_f32 v83, v90, v91
	global_store_dwordx4 v[92:93], v[80:83], off offset:256
	s_nop 1
	s_waitcnt vmcnt(15)
	v_lshlrev_b32_e32 v80, 16, v164
	v_and_b32_e32 v81, 0xffff0000, v164
	v_lshlrev_b32_e32 v82, 16, v165
	v_and_b32_e32 v83, 0xffff0000, v165
	v_pk_add_f32 v[78:79], v[78:79], v[82:83]
	v_pk_add_f32 v[76:77], v[76:77], v[80:81]
	v_lshlrev_b32_e32 v80, 16, v166
	v_and_b32_e32 v81, 0xffff0000, v166
	v_lshlrev_b32_e32 v82, 16, v167
	v_and_b32_e32 v83, 0xffff0000, v167
	v_pk_add_f32 v[82:83], v[74:75], v[82:83]
	v_pk_add_f32 v[74:75], v[72:73], v[80:81]
	v_cvt_pk_bf16_f32 v72, v76, v77
	v_lshl_add_u64 v[76:77], s[52:53], 0, v[194:195]
	v_cvt_pk_bf16_f32 v73, v78, v79
	v_cvt_pk_bf16_f32 v74, v74, v75
	v_cvt_pk_bf16_f32 v75, v82, v83
	v_lshl_add_u64 v[76:77], v[76:77], 0, v[184:185]
	global_store_dwordx4 v[76:77], v[72:75], off
	s_nop 1
	s_waitcnt vmcnt(15)
	v_lshlrev_b32_e32 v72, 16, v160
	v_and_b32_e32 v73, 0xffff0000, v160
	v_lshlrev_b32_e32 v74, 16, v161
	v_and_b32_e32 v75, 0xffff0000, v161
	v_pk_add_f32 v[70:71], v[70:71], v[74:75]
	v_pk_add_f32 v[68:69], v[68:69], v[72:73]
	v_lshlrev_b32_e32 v72, 16, v162
	v_and_b32_e32 v73, 0xffff0000, v162
	v_lshlrev_b32_e32 v74, 16, v163
	v_and_b32_e32 v75, 0xffff0000, v163
	v_pk_add_f32 v[74:75], v[66:67], v[74:75]
	v_pk_add_f32 v[66:67], v[64:65], v[72:73]
	v_cvt_pk_bf16_f32 v64, v68, v69
	v_cvt_pk_bf16_f32 v65, v70, v71
	s_nop 0
	v_cvt_pk_bf16_f32 v66, v66, v67
	v_cvt_pk_bf16_f32 v67, v74, v75
	global_store_dwordx4 v[76:77], v[64:67], off offset:256
	s_nop 1
	s_waitcnt vmcnt(15)
	v_lshlrev_b32_e32 v64, 16, v156
	v_and_b32_e32 v65, 0xffff0000, v156
	v_lshlrev_b32_e32 v66, 16, v157
	v_and_b32_e32 v67, 0xffff0000, v157
	v_pk_add_f32 v[62:63], v[62:63], v[66:67]
	v_pk_add_f32 v[60:61], v[60:61], v[64:65]
	v_lshlrev_b32_e32 v64, 16, v158
	v_and_b32_e32 v65, 0xffff0000, v158
	v_lshlrev_b32_e32 v66, 16, v159
	v_and_b32_e32 v67, 0xffff0000, v159
	v_pk_add_f32 v[66:67], v[58:59], v[66:67]
	v_pk_add_f32 v[58:59], v[56:57], v[64:65]
	v_cvt_pk_bf16_f32 v56, v60, v61
	v_lshl_add_u64 v[60:61], s[52:53], 0, v[192:193]
	v_cvt_pk_bf16_f32 v57, v62, v63
	v_cvt_pk_bf16_f32 v58, v58, v59
	v_cvt_pk_bf16_f32 v59, v66, v67
	v_lshl_add_u64 v[60:61], v[60:61], 0, v[184:185]
	global_store_dwordx4 v[60:61], v[56:59], off
	s_nop 1
	s_waitcnt vmcnt(15)
	v_lshlrev_b32_e32 v56, 16, v152
	v_and_b32_e32 v57, 0xffff0000, v152
	v_lshlrev_b32_e32 v58, 16, v153
	v_and_b32_e32 v59, 0xffff0000, v153
	v_pk_add_f32 v[54:55], v[54:55], v[58:59]
	v_pk_add_f32 v[52:53], v[52:53], v[56:57]
	v_lshlrev_b32_e32 v56, 16, v154
	v_and_b32_e32 v57, 0xffff0000, v154
	v_lshlrev_b32_e32 v58, 16, v155
	v_and_b32_e32 v59, 0xffff0000, v155
	v_pk_add_f32 v[58:59], v[50:51], v[58:59]
	v_pk_add_f32 v[50:51], v[48:49], v[56:57]
	v_cvt_pk_bf16_f32 v48, v52, v53
	v_cvt_pk_bf16_f32 v49, v54, v55
	s_nop 0
	v_cvt_pk_bf16_f32 v50, v50, v51
	v_cvt_pk_bf16_f32 v51, v58, v59
	global_store_dwordx4 v[60:61], v[48:51], off offset:256
	s_nop 1
	s_waitcnt vmcnt(15)
; __device__ __forceinline__ unsigned cvt_pk_bf16(float lo, float hi) { unsigned r; asm volatile("v_cvt_pk_bf16_f32 %0, %1, %2" : "=v"(r) : "v"(lo), "v"(hi)); return r; }
;     __device__ __forceinline__ void operator()(const f32x4 (&acc)[2][2][4][2], const Unit& u, int wr, int wc, int fr, int fq) const {
;     ...
; #pragma unroll
;             for (int ai = 0; ai < 2; ++ai)
; #pragma unroll
;                 for (int m = 0; m < 4; ++m)
; #pragma unroll
;                     for (int bj = 0; bj < 2; ++bj) { const u32x4 b = bv[ai][m][bj];
;                         const f32x4 v0 = acc[ai][bj][m][0] + (f32x4){__builtin_bit_cast(float, b.x << 16), __builtin_bit_cast(float, b.x & 0xffff0000u), __builtin_bit_cast(float, b.y << 16), __builtin_bit_cast(float, b.y & 0xffff0000u)};
;                         const f32x4 v1 = acc[ai][bj][m][1] + (f32x4){__builtin_bit_cast(float, b.z << 16), __builtin_bit_cast(float, b.z & 0xffff0000u), __builtin_bit_cast(float, b.w << 16), __builtin_bit_cast(float, b.w & 0xffff0000u)};
;                         u32x4 w; w.x = cvt_pk_bf16(v0[0], v0[1]); w.y = cvt_pk_bf16(v0[2], v0[3]); w.z = cvt_pk_bf16(v1[0], v1[1]); w.w = cvt_pk_bf16(v1[2], v1[3]);
;                         *(u32x4*)(outb + (size_t)(row0 + ai * HALF + m * 16) * ldc + col0 + bj * HALF) = w; }
	v_lshlrev_b32_e32 v48, 16, v148
	v_and_b32_e32 v49, 0xffff0000, v148
	v_lshlrev_b32_e32 v50, 16, v149
	v_and_b32_e32 v51, 0xffff0000, v149
	v_pk_add_f32 v[46:47], v[46:47], v[50:51]
	v_pk_add_f32 v[44:45], v[44:45], v[48:49]
	v_lshlrev_b32_e32 v48, 16, v150
	v_and_b32_e32 v49, 0xffff0000, v150
	v_lshlrev_b32_e32 v50, 16, v151
	v_and_b32_e32 v51, 0xffff0000, v151
	v_pk_add_f32 v[50:51], v[42:43], v[50:51]
	v_pk_add_f32 v[42:43], v[40:41], v[48:49]
	v_cvt_pk_bf16_f32 v40, v44, v45
	v_lshl_add_u64 v[44:45], s[52:53], 0, v[190:191]
	v_cvt_pk_bf16_f32 v41, v46, v47
	v_cvt_pk_bf16_f32 v42, v42, v43
	v_cvt_pk_bf16_f32 v43, v50, v51
	v_lshl_add_u64 v[44:45], v[44:45], 0, v[184:185]
	global_store_dwordx4 v[44:45], v[40:43], off
	s_nop 1
	s_waitcnt vmcnt(15)
	v_lshlrev_b32_e32 v40, 16, v144
	v_and_b32_e32 v41, 0xffff0000, v144
	v_lshlrev_b32_e32 v42, 16, v145
	v_and_b32_e32 v43, 0xffff0000, v145
	v_pk_add_f32 v[38:39], v[38:39], v[42:43]
	v_pk_add_f32 v[36:37], v[36:37], v[40:41]
	v_lshlrev_b32_e32 v40, 16, v146
	v_and_b32_e32 v41, 0xffff0000, v146
	v_lshlrev_b32_e32 v42, 16, v147
	v_and_b32_e32 v43, 0xffff0000, v147
	v_pk_add_f32 v[42:43], v[34:35], v[42:43]
	v_pk_add_f32 v[34:35], v[32:33], v[40:41]
	v_cvt_pk_bf16_f32 v32, v36, v37
	v_cvt_pk_bf16_f32 v33, v38, v39
	s_nop 0
	v_cvt_pk_bf16_f32 v34, v34, v35
	v_cvt_pk_bf16_f32 v35, v42, v43
	global_store_dwordx4 v[44:45], v[32:35], off offset:256
	s_nop 1
	s_waitcnt vmcnt(15)
	v_lshlrev_b32_e32 v32, 16, v140
	v_and_b32_e32 v33, 0xffff0000, v140
	v_lshlrev_b32_e32 v34, 16, v141
	v_and_b32_e32 v35, 0xffff0000, v141
	v_pk_add_f32 v[30:31], v[30:31], v[34:35]
	v_pk_add_f32 v[28:29], v[28:29], v[32:33]
	v_lshlrev_b32_e32 v32, 16, v142
	v_and_b32_e32 v33, 0xffff0000, v142
	v_lshlrev_b32_e32 v34, 16, v143
	v_and_b32_e32 v35, 0xffff0000, v143
	v_pk_add_f32 v[34:35], v[26:27], v[34:35]
	v_pk_add_f32 v[26:27], v[24:25], v[32:33]
	v_cvt_pk_bf16_f32 v24, v28, v29
	v_lshl_add_u64 v[28:29], s[52:53], 0, v[188:189]
	v_cvt_pk_bf16_f32 v25, v30, v31
	v_cvt_pk_bf16_f32 v26, v26, v27
	v_cvt_pk_bf16_f32 v27, v34, v35
	v_lshl_add_u64 v[28:29], v[28:29], 0, v[184:185]
	global_store_dwordx4 v[28:29], v[24:27], off
	s_nop 1
	s_waitcnt vmcnt(15)
	v_lshlrev_b32_e32 v24, 16, v136
	v_and_b32_e32 v25, 0xffff0000, v136
	v_lshlrev_b32_e32 v26, 16, v137
	v_and_b32_e32 v27, 0xffff0000, v137
	v_pk_add_f32 v[22:23], v[22:23], v[26:27]
	v_pk_add_f32 v[20:21], v[20:21], v[24:25]
	v_lshlrev_b32_e32 v24, 16, v138
	v_and_b32_e32 v25, 0xffff0000, v138
	v_lshlrev_b32_e32 v26, 16, v139
	v_and_b32_e32 v27, 0xffff0000, v139
	v_pk_add_f32 v[26:27], v[18:19], v[26:27]
	v_pk_add_f32 v[18:19], v[16:17], v[24:25]
	v_cvt_pk_bf16_f32 v16, v20, v21
	v_cvt_pk_bf16_f32 v17, v22, v23
	s_nop 0
	v_cvt_pk_bf16_f32 v18, v18, v19
	v_cvt_pk_bf16_f32 v19, v26, v27
	global_store_dwordx4 v[28:29], v[16:19], off offset:256
	s_nop 1
	s_waitcnt vmcnt(15)
	v_lshlrev_b32_e32 v16, 16, v132
	v_and_b32_e32 v17, 0xffff0000, v132
	v_lshlrev_b32_e32 v18, 16, v133
	v_and_b32_e32 v19, 0xffff0000, v133
	v_pk_add_f32 v[14:15], v[14:15], v[18:19]
	v_pk_add_f32 v[12:13], v[12:13], v[16:17]
	v_lshlrev_b32_e32 v16, 16, v134
	v_and_b32_e32 v17, 0xffff0000, v134
	v_lshlrev_b32_e32 v18, 16, v135
	v_and_b32_e32 v19, 0xffff0000, v135
	v_pk_add_f32 v[18:19], v[10:11], v[18:19]
	v_pk_add_f32 v[10:11], v[8:9], v[16:17]
	v_cvt_pk_bf16_f32 v8, v12, v13
	v_lshl_add_u64 v[12:13], s[52:53], 0, v[186:187]
	v_cvt_pk_bf16_f32 v9, v14, v15
	v_cvt_pk_bf16_f32 v10, v10, v11
	v_cvt_pk_bf16_f32 v11, v18, v19
	v_lshl_add_u64 v[12:13], v[12:13], 0, v[184:185]
	global_store_dwordx4 v[12:13], v[8:11], off
	s_nop 1
	s_waitcnt vmcnt(15)
	v_lshlrev_b32_e32 v8, 16, v128
	v_and_b32_e32 v9, 0xffff0000, v128
	v_lshlrev_b32_e32 v10, 16, v129
	v_and_b32_e32 v11, 0xffff0000, v129
	v_pk_add_f32 v[6:7], v[6:7], v[10:11]
	v_pk_add_f32 v[4:5], v[4:5], v[8:9]
	v_lshlrev_b32_e32 v8, 16, v130
	v_and_b32_e32 v9, 0xffff0000, v130
	v_lshlrev_b32_e32 v10, 16, v131
	v_and_b32_e32 v11, 0xffff0000, v131
	v_pk_add_f32 v[10:11], v[2:3], v[10:11]
	v_pk_add_f32 v[2:3], v[0:1], v[8:9]
	v_cvt_pk_bf16_f32 v0, v4, v5
	v_cvt_pk_bf16_f32 v1, v6, v7
	s_nop 0
	v_cvt_pk_bf16_f32 v2, v2, v3
	v_cvt_pk_bf16_f32 v3, v10, v11
	global_store_dwordx4 v[12:13], v[0:3], off offset:256
	s_cbranch_vccnz .LBB0_444
	s_andn2_b64 vcc, exec, s[10:11]
	s_cbranch_vccnz .LBB0_443
	s_barrier
	s_branch .LBB0_443

; __device__ __forceinline__ unsigned cvt_pk_bf16(float lo, float hi) { unsigned r; asm volatile("v_cvt_pk_bf16_f32 %0, %1, %2" : "=v"(r) : "v"(lo), "v"(hi)); return r; }
;     __device__ __forceinline__ void operator()(const f32x4 (&acc)[2][2][4][2], const Unit& u, int wr, int wc, int fr, int fq) const {
;     ...
;             u32x4 bv[2][4][2];
; #pragma unroll
;             for (int ai = 0; ai < 2; ++ai)
; #pragma unroll
;                 for (int m = 0; m < 4; ++m)
; #pragma unroll
;                     for (int bj = 0; bj < 2; ++bj) bv[ai][m][bj] = *(const u32x4*)(baseb + (size_t)(row0 + ai * HALF + m * 16) * ldc + col0 + bj * HALF);
;             asm volatile("" ::: "memory");
; #pragma unroll
;             for (int ai = 0; ai < 2; ++ai)
; #pragma unroll
;                 for (int m = 0; m < 4; ++m)
; #pragma unroll
;                     for (int bj = 0; bj < 2; ++bj) { const u32x4 b = bv[ai][m][bj];
;                         const f32x4 v0 = acc[ai][bj][m][0] + (f32x4){__builtin_bit_cast(float, b.x << 16), __builtin_bit_cast(float, b.x & 0xffff0000u), __builtin_bit_cast(float, b.y << 16), __builtin_bit_cast(float, b.y & 0xffff0000u)};
;                         const f32x4 v1 = acc[ai][bj][m][1] + (f32x4){__builtin_bit_cast(float, b.z << 16), __builtin_bit_cast(float, b.z & 0xffff0000u), __builtin_bit_cast(float, b.w << 16), __builtin_bit_cast(float, b.w & 0xffff0000u)};
;                         u32x4 w; w.x = cvt_pk_bf16(v0[0], v0[1]); w.y = cvt_pk_bf16(v0[2], v0[3]); w.z = cvt_pk_bf16(v1[0], v1[1]); w.w = cvt_pk_bf16(v1[2], v1[3]);
;                         *(u32x4*)(outb + (size_t)(row0 + ai * HALF + m * 16) * ldc + col0 + bj * HALF) = w; }
.LBB0_607:
	v_lshl_or_b32 v130, s24, 8, v201
	v_lshl_add_u32 v128, s70, 8, v199
	v_ashrrev_i32_e32 v131, 31, v130
	v_lshlrev_b64 v[184:185], 1, v[130:131]
	v_ashrrev_i32_e32 v129, 31, v128
	v_lshl_add_u64 v[130:131], s[44:45], 0, v[184:185]
	v_lshlrev_b64 v[132:133], 12, v[128:129]
	v_lshl_add_u64 v[134:135], v[130:131], 0, v[132:133]
	global_load_dwordx4 v[206:209], v[134:135], off
	global_load_dwordx4 v[210:213], v[134:135], off offset:256
	v_or_b32_e32 v134, 16, v128
	v_ashrrev_i32_e32 v135, 31, v134
	v_lshlrev_b64 v[230:231], 12, v[134:135]
	v_lshl_add_u64 v[134:135], v[130:131], 0, v[230:231]
	global_load_dwordx4 v[214:217], v[134:135], off
	global_load_dwordx4 v[218:221], v[134:135], off offset:256
	v_or_b32_e32 v136, 32, v128
	v_or_b32_e32 v128, 48, v128
	s_mov_b64 s[24:25], 0x80000
	s_mov_b64 s[72:73], 0x90000
	s_mov_b64 s[74:75], 0xa0000
	v_ashrrev_i32_e32 v137, 31, v136
	v_ashrrev_i32_e32 v129, 31, v128
	v_lshlrev_b64 v[196:197], 12, v[136:137]
	v_lshlrev_b64 v[194:195], 12, v[128:129]
	v_lshl_add_u64 v[192:193], v[132:133], 0, s[24:25]
	v_lshl_add_u64 v[190:191], v[132:133], 0, s[72:73]
	v_lshl_add_u64 v[188:189], v[132:133], 0, s[74:75]
	v_lshl_add_u64 v[186:187], v[132:133], 0, s[60:61]
	v_lshl_add_u64 v[128:129], s[44:45], 0, v[132:133]
	v_lshl_add_u64 v[132:133], v[130:131], 0, v[196:197]
	v_lshl_add_u64 v[134:135], v[130:131], 0, v[194:195]
	v_lshl_add_u64 v[136:137], v[130:131], 0, v[192:193]
	v_lshl_add_u64 v[138:139], v[130:131], 0, v[190:191]
	v_lshl_add_u64 v[232:233], v[130:131], 0, v[188:189]
	v_lshl_add_u64 v[130:131], v[130:131], 0, v[186:187]
	v_lshl_add_u64 v[234:235], v[128:129], 0, v[184:185]
	global_load_dwordx4 v[222:225], v[132:133], off
	global_load_dwordx4 v[226:229], v[132:133], off offset:256
	global_load_dwordx4 v[164:167], v[134:135], off
	global_load_dwordx4 v[160:163], v[134:135], off offset:256
	global_load_dwordx4 v[156:159], v[136:137], off
	global_load_dwordx4 v[152:155], v[136:137], off offset:256
	global_load_dwordx4 v[148:151], v[138:139], off
	global_load_dwordx4 v[144:147], v[138:139], off offset:256
	global_load_dwordx4 v[140:143], v[232:233], off
	s_nop 0
	global_load_dwordx4 v[136:139], v[232:233], off offset:256
	global_load_dwordx4 v[132:135], v[130:131], off
	s_nop 0
	global_load_dwordx4 v[128:131], v[130:131], off offset:256
	s_andn2_b64 vcc, exec, s[6:7]
	s_mov_b64 s[6:7], -1
	s_waitcnt vmcnt(15)
	v_lshlrev_b32_e32 v232, 16, v206
	v_and_b32_e32 v233, 0xffff0000, v206
	v_lshlrev_b32_e32 v206, 16, v207
	v_and_b32_e32 v207, 0xffff0000, v207
	v_lshlrev_b32_e32 v236, 16, v208
	v_and_b32_e32 v237, 0xffff0000, v208
	v_lshlrev_b32_e32 v208, 16, v209
	v_and_b32_e32 v209, 0xffff0000, v209
	s_waitcnt vmcnt(14)
	v_lshlrev_b32_e32 v240, 16, v212
	v_and_b32_e32 v241, 0xffff0000, v212
	v_lshlrev_b32_e32 v212, 16, v213
	v_and_b32_e32 v213, 0xffff0000, v213
	v_lshlrev_b32_e32 v238, 16, v210
	v_and_b32_e32 v239, 0xffff0000, v210
	v_lshlrev_b32_e32 v210, 16, v211
	v_and_b32_e32 v211, 0xffff0000, v211
	v_pk_add_f32 v[126:127], v[126:127], v[206:207]
	v_pk_add_f32 v[124:125], v[124:125], v[232:233]
	v_pk_add_f32 v[122:123], v[122:123], v[208:209]
	v_pk_add_f32 v[120:121], v[120:121], v[236:237]
	v_pk_add_f32 v[206:207], v[106:107], v[212:213]
	v_pk_add_f32 v[208:209], v[104:105], v[240:241]
	v_cvt_pk_bf16_f32 v104, v124, v125
	v_cvt_pk_bf16_f32 v105, v126, v127
	v_cvt_pk_bf16_f32 v106, v120, v121
	v_cvt_pk_bf16_f32 v107, v122, v123
	s_waitcnt vmcnt(13)
	v_lshlrev_b32_e32 v244, 16, v216
	v_and_b32_e32 v245, 0xffff0000, v216
	v_pk_add_f32 v[114:115], v[114:115], v[210:211]
	v_pk_add_f32 v[112:113], v[112:113], v[238:239]
	global_store_dwordx4 v[234:235], v[104:107], off
	v_lshlrev_b32_e32 v242, 16, v214
	v_and_b32_e32 v243, 0xffff0000, v214
	v_cvt_pk_bf16_f32 v104, v112, v113
	v_cvt_pk_bf16_f32 v105, v114, v115
	v_cvt_pk_bf16_f32 v106, v208, v209
	v_cvt_pk_bf16_f32 v107, v206, v207
	v_lshlrev_b32_e32 v214, 16, v215
	v_and_b32_e32 v215, 0xffff0000, v215
	v_lshlrev_b32_e32 v216, 16, v217
	global_store_dwordx4 v[234:235], v[104:107], off offset:256
	v_and_b32_e32 v217, 0xffff0000, v217
	v_pk_add_f32 v[118:119], v[118:119], v[214:215]
	v_pk_add_f32 v[106:107], v[108:109], v[244:245]
	v_lshl_add_u64 v[108:109], s[44:45], 0, v[230:231]
	v_pk_add_f32 v[116:117], v[116:117], v[242:243]
	v_pk_add_f32 v[110:111], v[110:111], v[216:217]
	v_cvt_pk_bf16_f32 v104, v116, v117
	v_cvt_pk_bf16_f32 v105, v118, v119
	v_cvt_pk_bf16_f32 v106, v106, v107
	v_lshl_add_u64 v[108:109], v[108:109], 0, v[184:185]
	v_cvt_pk_bf16_f32 v107, v110, v111
	global_store_dwordx4 v[108:109], v[104:107], off
	s_nop 1
	s_waitcnt vmcnt(15)
	v_lshlrev_b32_e32 v104, 16, v218
	v_and_b32_e32 v105, 0xffff0000, v218
	v_lshlrev_b32_e32 v106, 16, v219
	v_and_b32_e32 v107, 0xffff0000, v219
	v_pk_add_f32 v[102:103], v[102:103], v[106:107]
	v_pk_add_f32 v[100:101], v[100:101], v[104:105]
	v_lshlrev_b32_e32 v104, 16, v220
	v_and_b32_e32 v105, 0xffff0000, v220
	v_lshlrev_b32_e32 v106, 16, v221
	v_and_b32_e32 v107, 0xffff0000, v221
	v_pk_add_f32 v[106:107], v[98:99], v[106:107]
	v_pk_add_f32 v[98:99], v[96:97], v[104:105]
	v_cvt_pk_bf16_f32 v96, v100, v101
	v_cvt_pk_bf16_f32 v97, v102, v103
	s_nop 0
	v_cvt_pk_bf16_f32 v98, v98, v99
	v_cvt_pk_bf16_f32 v99, v106, v107
	global_store_dwordx4 v[108:109], v[96:99], off offset:256
	s_nop 1
	s_waitcnt vmcnt(15)
; __device__ __forceinline__ unsigned cvt_pk_bf16(float lo, float hi) { unsigned r; asm volatile("v_cvt_pk_bf16_f32 %0, %1, %2" : "=v"(r) : "v"(lo), "v"(hi)); return r; }
;     __device__ __forceinline__ void operator()(const f32x4 (&acc)[2][2][4][2], const Unit& u, int wr, int wc, int fr, int fq) const {
;     ...
; #pragma unroll
;             for (int ai = 0; ai < 2; ++ai)
; #pragma unroll
;                 for (int m = 0; m < 4; ++m)
; #pragma unroll
;                     for (int bj = 0; bj < 2; ++bj) { const u32x4 b = bv[ai][m][bj];
;                         const f32x4 v0 = acc[ai][bj][m][0] + (f32x4){__builtin_bit_cast(float, b.x << 16), __builtin_bit_cast(float, b.x & 0xffff0000u), __builtin_bit_cast(float, b.y << 16), __builtin_bit_cast(float, b.y & 0xffff0000u)};
;                         const f32x4 v1 = acc[ai][bj][m][1] + (f32x4){__builtin_bit_cast(float, b.z << 16), __builtin_bit_cast(float, b.z & 0xffff0000u), __builtin_bit_cast(float, b.w << 16), __builtin_bit_cast(float, b.w & 0xffff0000u)};
;                         u32x4 w; w.x = cvt_pk_bf16(v0[0], v0[1]); w.y = cvt_pk_bf16(v0[2], v0[3]); w.z = cvt_pk_bf16(v1[0], v1[1]); w.w = cvt_pk_bf16(v1[2], v1[3]);
;                         *(u32x4*)(outb + (size_t)(row0 + ai * HALF + m * 16) * ldc + col0 + bj * HALF) = w; }
	v_lshlrev_b32_e32 v96, 16, v222
	v_and_b32_e32 v97, 0xffff0000, v222
	v_lshlrev_b32_e32 v98, 16, v223
	v_and_b32_e32 v99, 0xffff0000, v223
	v_pk_add_f32 v[94:95], v[94:95], v[98:99]
	v_pk_add_f32 v[92:93], v[92:93], v[96:97]
	v_lshlrev_b32_e32 v96, 16, v224
	v_and_b32_e32 v97, 0xffff0000, v224
	v_lshlrev_b32_e32 v98, 16, v225
	v_and_b32_e32 v99, 0xffff0000, v225
	v_pk_add_f32 v[98:99], v[90:91], v[98:99]
	v_pk_add_f32 v[90:91], v[88:89], v[96:97]
	v_cvt_pk_bf16_f32 v88, v92, v93
	v_lshl_add_u64 v[92:93], s[44:45], 0, v[196:197]
	v_cvt_pk_bf16_f32 v89, v94, v95
	v_cvt_pk_bf16_f32 v90, v90, v91
	v_cvt_pk_bf16_f32 v91, v98, v99
	v_lshl_add_u64 v[92:93], v[92:93], 0, v[184:185]
	global_store_dwordx4 v[92:93], v[88:91], off
	s_nop 1
	s_waitcnt vmcnt(15)
	v_lshlrev_b32_e32 v88, 16, v226
	v_and_b32_e32 v89, 0xffff0000, v226
	v_lshlrev_b32_e32 v90, 16, v227
	v_and_b32_e32 v91, 0xffff0000, v227
	v_pk_add_f32 v[86:87], v[86:87], v[90:91]
	v_pk_add_f32 v[84:85], v[84:85], v[88:89]
	v_lshlrev_b32_e32 v88, 16, v228
	v_and_b32_e32 v89, 0xffff0000, v228
	v_lshlrev_b32_e32 v90, 16, v229
	v_and_b32_e32 v91, 0xffff0000, v229
	v_pk_add_f32 v[90:91], v[82:83], v[90:91]
	v_pk_add_f32 v[82:83], v[80:81], v[88:89]
	v_cvt_pk_bf16_f32 v80, v84, v85
	v_cvt_pk_bf16_f32 v81, v86, v87
	s_nop 0
	v_cvt_pk_bf16_f32 v82, v82, v83
	v_cvt_pk_bf16_f32 v83, v90, v91
	global_store_dwordx4 v[92:93], v[80:83], off offset:256
	s_nop 1
	s_waitcnt vmcnt(15)
	v_lshlrev_b32_e32 v80, 16, v164
	v_and_b32_e32 v81, 0xffff0000, v164
	v_lshlrev_b32_e32 v82, 16, v165
	v_and_b32_e32 v83, 0xffff0000, v165
	v_pk_add_f32 v[78:79], v[78:79], v[82:83]
	v_pk_add_f32 v[76:77], v[76:77], v[80:81]
	v_lshlrev_b32_e32 v80, 16, v166
	v_and_b32_e32 v81, 0xffff0000, v166
	v_lshlrev_b32_e32 v82, 16, v167
	v_and_b32_e32 v83, 0xffff0000, v167
	v_pk_add_f32 v[82:83], v[74:75], v[82:83]
	v_pk_add_f32 v[74:75], v[72:73], v[80:81]
	v_cvt_pk_bf16_f32 v72, v76, v77
	v_lshl_add_u64 v[76:77], s[44:45], 0, v[194:195]
	v_cvt_pk_bf16_f32 v73, v78, v79
	v_cvt_pk_bf16_f32 v74, v74, v75
	v_cvt_pk_bf16_f32 v75, v82, v83
	v_lshl_add_u64 v[76:77], v[76:77], 0, v[184:185]
	global_store_dwordx4 v[76:77], v[72:75], off
	s_nop 1
	s_waitcnt vmcnt(15)
	v_lshlrev_b32_e32 v72, 16, v160
	v_and_b32_e32 v73, 0xffff0000, v160
	v_lshlrev_b32_e32 v74, 16, v161
	v_and_b32_e32 v75, 0xffff0000, v161
	v_pk_add_f32 v[70:71], v[70:71], v[74:75]
	v_pk_add_f32 v[68:69], v[68:69], v[72:73]
	v_lshlrev_b32_e32 v72, 16, v162
	v_and_b32_e32 v73, 0xffff0000, v162
	v_lshlrev_b32_e32 v74, 16, v163
	v_and_b32_e32 v75, 0xffff0000, v163
	v_pk_add_f32 v[74:75], v[66:67], v[74:75]
	v_pk_add_f32 v[66:67], v[64:65], v[72:73]
	v_cvt_pk_bf16_f32 v64, v68, v69
	v_cvt_pk_bf16_f32 v65, v70, v71
	s_nop 0
	v_cvt_pk_bf16_f32 v66, v66, v67
	v_cvt_pk_bf16_f32 v67, v74, v75
	global_store_dwordx4 v[76:77], v[64:67], off offset:256
	s_nop 1
	s_waitcnt vmcnt(15)
	v_lshlrev_b32_e32 v64, 16, v156
	v_and_b32_e32 v65, 0xffff0000, v156
	v_lshlrev_b32_e32 v66, 16, v157
	v_and_b32_e32 v67, 0xffff0000, v157
	v_pk_add_f32 v[62:63], v[62:63], v[66:67]
	v_pk_add_f32 v[60:61], v[60:61], v[64:65]
	v_lshlrev_b32_e32 v64, 16, v158
	v_and_b32_e32 v65, 0xffff0000, v158
	v_lshlrev_b32_e32 v66, 16, v159
	v_and_b32_e32 v67, 0xffff0000, v159
	v_pk_add_f32 v[66:67], v[58:59], v[66:67]
	v_pk_add_f32 v[58:59], v[56:57], v[64:65]
	v_cvt_pk_bf16_f32 v56, v60, v61
	v_lshl_add_u64 v[60:61], s[44:45], 0, v[192:193]
	v_cvt_pk_bf16_f32 v57, v62, v63
	v_cvt_pk_bf16_f32 v58, v58, v59
	v_cvt_pk_bf16_f32 v59, v66, v67
	v_lshl_add_u64 v[60:61], v[60:61], 0, v[184:185]
	global_store_dwordx4 v[60:61], v[56:59], off
	s_nop 1
	s_waitcnt vmcnt(15)
	v_lshlrev_b32_e32 v56, 16, v152
	v_and_b32_e32 v57, 0xffff0000, v152
	v_lshlrev_b32_e32 v58, 16, v153
	v_and_b32_e32 v59, 0xffff0000, v153
	v_pk_add_f32 v[54:55], v[54:55], v[58:59]
	v_pk_add_f32 v[52:53], v[52:53], v[56:57]
	v_lshlrev_b32_e32 v56, 16, v154
	v_and_b32_e32 v57, 0xffff0000, v154
	v_lshlrev_b32_e32 v58, 16, v155
	v_and_b32_e32 v59, 0xffff0000, v155
	v_pk_add_f32 v[58:59], v[50:51], v[58:59]
	v_pk_add_f32 v[50:51], v[48:49], v[56:57]
	v_cvt_pk_bf16_f32 v48, v52, v53
	v_cvt_pk_bf16_f32 v49, v54, v55
	s_nop 0
	v_cvt_pk_bf16_f32 v50, v50, v51
	v_cvt_pk_bf16_f32 v51, v58, v59
	global_store_dwordx4 v[60:61], v[48:51], off offset:256
	s_nop 1
	s_waitcnt vmcnt(15)
; __device__ __forceinline__ unsigned cvt_pk_bf16(float lo, float hi) { unsigned r; asm volatile("v_cvt_pk_bf16_f32 %0, %1, %2" : "=v"(r) : "v"(lo), "v"(hi)); return r; }
;     __device__ __forceinline__ void operator()(const f32x4 (&acc)[2][2][4][2], const Unit& u, int wr, int wc, int fr, int fq) const {
;     ...
; #pragma unroll
;             for (int ai = 0; ai < 2; ++ai)
; #pragma unroll
;                 for (int m = 0; m < 4; ++m)
; #pragma unroll
;                     for (int bj = 0; bj < 2; ++bj) { const u32x4 b = bv[ai][m][bj];
;                         const f32x4 v0 = acc[ai][bj][m][0] + (f32x4){__builtin_bit_cast(float, b.x << 16), __builtin_bit_cast(float, b.x & 0xffff0000u), __builtin_bit_cast(float, b.y << 16), __builtin_bit_cast(float, b.y & 0xffff0000u)};
;                         const f32x4 v1 = acc[ai][bj][m][1] + (f32x4){__builtin_bit_cast(float, b.z << 16), __builtin_bit_cast(float, b.z & 0xffff0000u), __builtin_bit_cast(float, b.w << 16), __builtin_bit_cast(float, b.w & 0xffff0000u)};
;                         u32x4 w; w.x = cvt_pk_bf16(v0[0], v0[1]); w.y = cvt_pk_bf16(v0[2], v0[3]); w.z = cvt_pk_bf16(v1[0], v1[1]); w.w = cvt_pk_bf16(v1[2], v1[3]);
;                         *(u32x4*)(outb + (size_t)(row0 + ai * HALF + m * 16) * ldc + col0 + bj * HALF) = w; }
	v_lshlrev_b32_e32 v48, 16, v148
	v_and_b32_e32 v49, 0xffff0000, v148
	v_lshlrev_b32_e32 v50, 16, v149
	v_and_b32_e32 v51, 0xffff0000, v149
	v_pk_add_f32 v[46:47], v[46:47], v[50:51]
	v_pk_add_f32 v[44:45], v[44:45], v[48:49]
	v_lshlrev_b32_e32 v48, 16, v150
	v_and_b32_e32 v49, 0xffff0000, v150
	v_lshlrev_b32_e32 v50, 16, v151
	v_and_b32_e32 v51, 0xffff0000, v151
	v_pk_add_f32 v[50:51], v[42:43], v[50:51]
	v_pk_add_f32 v[42:43], v[40:41], v[48:49]
	v_cvt_pk_bf16_f32 v40, v44, v45
	v_lshl_add_u64 v[44:45], s[44:45], 0, v[190:191]
	v_cvt_pk_bf16_f32 v41, v46, v47
	v_cvt_pk_bf16_f32 v42, v42, v43
	v_cvt_pk_bf16_f32 v43, v50, v51
	v_lshl_add_u64 v[44:45], v[44:45], 0, v[184:185]
	global_store_dwordx4 v[44:45], v[40:43], off
	s_nop 1
	s_waitcnt vmcnt(15)
	v_lshlrev_b32_e32 v40, 16, v144
	v_and_b32_e32 v41, 0xffff0000, v144
	v_lshlrev_b32_e32 v42, 16, v145
	v_and_b32_e32 v43, 0xffff0000, v145
	v_pk_add_f32 v[38:39], v[38:39], v[42:43]
	v_pk_add_f32 v[36:37], v[36:37], v[40:41]
	v_lshlrev_b32_e32 v40, 16, v146
	v_and_b32_e32 v41, 0xffff0000, v146
	v_lshlrev_b32_e32 v42, 16, v147
	v_and_b32_e32 v43, 0xffff0000, v147
	v_pk_add_f32 v[42:43], v[34:35], v[42:43]
	v_pk_add_f32 v[34:35], v[32:33], v[40:41]
	v_cvt_pk_bf16_f32 v32, v36, v37
	v_cvt_pk_bf16_f32 v33, v38, v39
	s_nop 0
	v_cvt_pk_bf16_f32 v34, v34, v35
	v_cvt_pk_bf16_f32 v35, v42, v43
	global_store_dwordx4 v[44:45], v[32:35], off offset:256
	s_nop 1
	s_waitcnt vmcnt(15)
	v_lshlrev_b32_e32 v32, 16, v140
	v_and_b32_e32 v33, 0xffff0000, v140
	v_lshlrev_b32_e32 v34, 16, v141
	v_and_b32_e32 v35, 0xffff0000, v141
	v_pk_add_f32 v[30:31], v[30:31], v[34:35]
	v_pk_add_f32 v[28:29], v[28:29], v[32:33]
	v_lshlrev_b32_e32 v32, 16, v142
	v_and_b32_e32 v33, 0xffff0000, v142
	v_lshlrev_b32_e32 v34, 16, v143
	v_and_b32_e32 v35, 0xffff0000, v143
	v_pk_add_f32 v[34:35], v[26:27], v[34:35]
	v_pk_add_f32 v[26:27], v[24:25], v[32:33]
	v_cvt_pk_bf16_f32 v24, v28, v29
	v_lshl_add_u64 v[28:29], s[44:45], 0, v[188:189]
	v_cvt_pk_bf16_f32 v25, v30, v31
	v_cvt_pk_bf16_f32 v26, v26, v27
	v_cvt_pk_bf16_f32 v27, v34, v35
	v_lshl_add_u64 v[28:29], v[28:29], 0, v[184:185]
	global_store_dwordx4 v[28:29], v[24:27], off
	s_nop 1
	s_waitcnt vmcnt(15)
	v_lshlrev_b32_e32 v24, 16, v136
	v_and_b32_e32 v25, 0xffff0000, v136
	v_lshlrev_b32_e32 v26, 16, v137
	v_and_b32_e32 v27, 0xffff0000, v137
	v_pk_add_f32 v[22:23], v[22:23], v[26:27]
	v_pk_add_f32 v[20:21], v[20:21], v[24:25]
	v_lshlrev_b32_e32 v24, 16, v138
	v_and_b32_e32 v25, 0xffff0000, v138
	v_lshlrev_b32_e32 v26, 16, v139
	v_and_b32_e32 v27, 0xffff0000, v139
	v_pk_add_f32 v[26:27], v[18:19], v[26:27]
	v_pk_add_f32 v[18:19], v[16:17], v[24:25]
	v_cvt_pk_bf16_f32 v16, v20, v21
	v_cvt_pk_bf16_f32 v17, v22, v23
	s_nop 0
	v_cvt_pk_bf16_f32 v18, v18, v19
	v_cvt_pk_bf16_f32 v19, v26, v27
	global_store_dwordx4 v[28:29], v[16:19], off offset:256
	s_nop 1
	s_waitcnt vmcnt(15)
	v_lshlrev_b32_e32 v16, 16, v132
	v_and_b32_e32 v17, 0xffff0000, v132
	v_lshlrev_b32_e32 v18, 16, v133
	v_and_b32_e32 v19, 0xffff0000, v133
	v_pk_add_f32 v[14:15], v[14:15], v[18:19]
	v_pk_add_f32 v[12:13], v[12:13], v[16:17]
	v_lshlrev_b32_e32 v16, 16, v134
	v_and_b32_e32 v17, 0xffff0000, v134
	v_lshlrev_b32_e32 v18, 16, v135
	v_and_b32_e32 v19, 0xffff0000, v135
	v_pk_add_f32 v[18:19], v[10:11], v[18:19]
	v_pk_add_f32 v[10:11], v[8:9], v[16:17]
	v_cvt_pk_bf16_f32 v8, v12, v13
	v_lshl_add_u64 v[12:13], s[44:45], 0, v[186:187]
	v_cvt_pk_bf16_f32 v9, v14, v15
	v_cvt_pk_bf16_f32 v10, v10, v11
	v_cvt_pk_bf16_f32 v11, v18, v19
	v_lshl_add_u64 v[12:13], v[12:13], 0, v[184:185]
	global_store_dwordx4 v[12:13], v[8:11], off
	s_nop 1
	s_waitcnt vmcnt(15)
	v_lshlrev_b32_e32 v8, 16, v128
	v_and_b32_e32 v9, 0xffff0000, v128
	v_lshlrev_b32_e32 v10, 16, v129
	v_and_b32_e32 v11, 0xffff0000, v129
	v_pk_add_f32 v[6:7], v[6:7], v[10:11]
	v_pk_add_f32 v[4:5], v[4:5], v[8:9]
	v_lshlrev_b32_e32 v8, 16, v130
	v_and_b32_e32 v9, 0xffff0000, v130
	v_lshlrev_b32_e32 v10, 16, v131
	v_and_b32_e32 v11, 0xffff0000, v131
	v_pk_add_f32 v[10:11], v[2:3], v[10:11]
	v_pk_add_f32 v[2:3], v[0:1], v[8:9]
	v_cvt_pk_bf16_f32 v0, v4, v5
	v_cvt_pk_bf16_f32 v1, v6, v7
	s_nop 0
	v_cvt_pk_bf16_f32 v2, v2, v3
	v_cvt_pk_bf16_f32 v3, v10, v11
	global_store_dwordx4 v[12:13], v[0:3], off offset:256
	s_cbranch_vccnz .LBB0_596
	s_andn2_b64 vcc, exec, s[8:9]
	s_cbranch_vccnz .LBB0_595
	s_barrier
	s_branch .LBB0_595

; __device__ __forceinline__ unsigned cvt_pk_bf16(float lo, float hi) { unsigned r; asm volatile("v_cvt_pk_bf16_f32 %0, %1, %2" : "=v"(r) : "v"(lo), "v"(hi)); return r; }
;     __device__ __forceinline__ void operator()(const f32x4 (&acc)[2][2][4][2], const Unit& u, int wr, int wc, int fr, int fq) const {
;     ...
;             u32x4 bv[2][4][2];
; #pragma unroll
;             for (int ai = 0; ai < 2; ++ai)
; #pragma unroll
;                 for (int m = 0; m < 4; ++m)
; #pragma unroll
;                     for (int bj = 0; bj < 2; ++bj) bv[ai][m][bj] = *(const u32x4*)(baseb + (size_t)(row0 + ai * HALF + m * 16) * ldc + col0 + bj * HALF);
;             asm volatile("" ::: "memory");
; #pragma unroll
;             for (int ai = 0; ai < 2; ++ai)
; #pragma unroll
;                 for (int m = 0; m < 4; ++m)
; #pragma unroll
;                     for (int bj = 0; bj < 2; ++bj) { const u32x4 b = bv[ai][m][bj];
;                         const f32x4 v0 = acc[ai][bj][m][0] + (f32x4){__builtin_bit_cast(float, b.x << 16), __builtin_bit_cast(float, b.x & 0xffff0000u), __builtin_bit_cast(float, b.y << 16), __builtin_bit_cast(float, b.y & 0xffff0000u)};
;                         const f32x4 v1 = acc[ai][bj][m][1] + (f32x4){__builtin_bit_cast(float, b.z << 16), __builtin_bit_cast(float, b.z & 0xffff0000u), __builtin_bit_cast(float, b.w << 16), __builtin_bit_cast(float, b.w & 0xffff0000u)};
;                         u32x4 w; w.x = cvt_pk_bf16(v0[0], v0[1]); w.y = cvt_pk_bf16(v0[2], v0[3]); w.z = cvt_pk_bf16(v1[0], v1[1]); w.w = cvt_pk_bf16(v1[2], v1[3]);
;                         *(u32x4*)(outb + (size_t)(row0 + ai * HALF + m * 16) * ldc + col0 + bj * HALF) = w; }
.LBB0_1056:
	v_lshl_or_b32 v130, s24, 8, v201
	v_lshl_add_u32 v128, s50, 8, v199
	v_ashrrev_i32_e32 v131, 31, v130
	v_lshlrev_b64 v[184:185], 1, v[130:131]
	v_ashrrev_i32_e32 v129, 31, v128
	v_lshl_add_u64 v[130:131], s[52:53], 0, v[184:185]
	v_lshlrev_b64 v[132:133], 12, v[128:129]
	v_lshl_add_u64 v[134:135], v[130:131], 0, v[132:133]
	global_load_dwordx4 v[206:209], v[134:135], off
	global_load_dwordx4 v[210:213], v[134:135], off offset:256
	v_or_b32_e32 v134, 16, v128
	v_ashrrev_i32_e32 v135, 31, v134
	v_lshlrev_b64 v[230:231], 12, v[134:135]
	v_lshl_add_u64 v[134:135], v[130:131], 0, v[230:231]
	global_load_dwordx4 v[214:217], v[134:135], off
	global_load_dwordx4 v[218:221], v[134:135], off offset:256
	v_or_b32_e32 v136, 32, v128
	v_or_b32_e32 v128, 48, v128
	v_ashrrev_i32_e32 v137, 31, v136
	v_ashrrev_i32_e32 v129, 31, v128
	v_lshlrev_b64 v[196:197], 12, v[136:137]
	v_lshlrev_b64 v[194:195], 12, v[128:129]
	v_lshl_add_u64 v[192:193], v[132:133], 0, s[8:9]
	v_lshl_add_u64 v[190:191], v[132:133], 0, s[18:19]
	v_lshl_add_u64 v[188:189], v[132:133], 0, s[20:21]
	v_lshl_add_u64 v[186:187], v[132:133], 0, s[22:23]
	v_lshl_add_u64 v[128:129], s[52:53], 0, v[132:133]
	v_lshl_add_u64 v[132:133], v[130:131], 0, v[196:197]
	v_lshl_add_u64 v[134:135], v[130:131], 0, v[194:195]
	v_lshl_add_u64 v[136:137], v[130:131], 0, v[192:193]
	v_lshl_add_u64 v[138:139], v[130:131], 0, v[190:191]
	v_lshl_add_u64 v[232:233], v[130:131], 0, v[188:189]
	v_lshl_add_u64 v[130:131], v[130:131], 0, v[186:187]
	v_lshl_add_u64 v[234:235], v[128:129], 0, v[184:185]
	global_load_dwordx4 v[222:225], v[132:133], off
	global_load_dwordx4 v[226:229], v[132:133], off offset:256
	global_load_dwordx4 v[164:167], v[134:135], off
	global_load_dwordx4 v[160:163], v[134:135], off offset:256
	global_load_dwordx4 v[156:159], v[136:137], off
	global_load_dwordx4 v[152:155], v[136:137], off offset:256
	global_load_dwordx4 v[148:151], v[138:139], off
	global_load_dwordx4 v[144:147], v[138:139], off offset:256
	global_load_dwordx4 v[140:143], v[232:233], off
	s_nop 0
	global_load_dwordx4 v[136:139], v[232:233], off offset:256
	global_load_dwordx4 v[132:135], v[130:131], off
	s_nop 0
	global_load_dwordx4 v[128:131], v[130:131], off offset:256
	s_andn2_b64 vcc, exec, s[6:7]
	s_mov_b64 s[6:7], -1
	s_waitcnt vmcnt(15)
	v_lshlrev_b32_e32 v232, 16, v206
	v_and_b32_e32 v233, 0xffff0000, v206
	v_lshlrev_b32_e32 v206, 16, v207
	v_and_b32_e32 v207, 0xffff0000, v207
	v_lshlrev_b32_e32 v236, 16, v208
	v_and_b32_e32 v237, 0xffff0000, v208
	v_lshlrev_b32_e32 v208, 16, v209
	v_and_b32_e32 v209, 0xffff0000, v209
	s_waitcnt vmcnt(14)
	v_lshlrev_b32_e32 v240, 16, v212
	v_and_b32_e32 v241, 0xffff0000, v212
	v_lshlrev_b32_e32 v212, 16, v213
	v_and_b32_e32 v213, 0xffff0000, v213
	v_lshlrev_b32_e32 v238, 16, v210
	v_and_b32_e32 v239, 0xffff0000, v210
	v_lshlrev_b32_e32 v210, 16, v211
	v_and_b32_e32 v211, 0xffff0000, v211
	v_pk_add_f32 v[126:127], v[126:127], v[206:207]
	v_pk_add_f32 v[124:125], v[124:125], v[232:233]
	v_pk_add_f32 v[122:123], v[122:123], v[208:209]
	v_pk_add_f32 v[120:121], v[120:121], v[236:237]
	v_pk_add_f32 v[206:207], v[106:107], v[212:213]
	v_pk_add_f32 v[208:209], v[104:105], v[240:241]
	v_cvt_pk_bf16_f32 v104, v124, v125
	v_cvt_pk_bf16_f32 v105, v126, v127
	v_cvt_pk_bf16_f32 v106, v120, v121
	v_cvt_pk_bf16_f32 v107, v122, v123
	s_waitcnt vmcnt(13)
	v_lshlrev_b32_e32 v244, 16, v216
	v_and_b32_e32 v245, 0xffff0000, v216
	v_pk_add_f32 v[114:115], v[114:115], v[210:211]
	v_pk_add_f32 v[112:113], v[112:113], v[238:239]
	global_store_dwordx4 v[234:235], v[104:107], off
	v_lshlrev_b32_e32 v242, 16, v214
	v_and_b32_e32 v243, 0xffff0000, v214
	v_cvt_pk_bf16_f32 v104, v112, v113
	v_cvt_pk_bf16_f32 v105, v114, v115
	v_cvt_pk_bf16_f32 v106, v208, v209
	v_cvt_pk_bf16_f32 v107, v206, v207
	v_lshlrev_b32_e32 v214, 16, v215
	v_and_b32_e32 v215, 0xffff0000, v215
	v_lshlrev_b32_e32 v216, 16, v217
	global_store_dwordx4 v[234:235], v[104:107], off offset:256
	v_and_b32_e32 v217, 0xffff0000, v217
	v_pk_add_f32 v[118:119], v[118:119], v[214:215]
	v_pk_add_f32 v[106:107], v[108:109], v[244:245]
	v_lshl_add_u64 v[108:109], s[52:53], 0, v[230:231]
	v_pk_add_f32 v[116:117], v[116:117], v[242:243]
	v_pk_add_f32 v[110:111], v[110:111], v[216:217]
	v_cvt_pk_bf16_f32 v104, v116, v117
	v_cvt_pk_bf16_f32 v105, v118, v119
	v_cvt_pk_bf16_f32 v106, v106, v107
	v_lshl_add_u64 v[108:109], v[108:109], 0, v[184:185]
	v_cvt_pk_bf16_f32 v107, v110, v111
	global_store_dwordx4 v[108:109], v[104:107], off
	s_nop 1
	s_waitcnt vmcnt(15)
	v_lshlrev_b32_e32 v104, 16, v218
	v_and_b32_e32 v105, 0xffff0000, v218
	v_lshlrev_b32_e32 v106, 16, v219
	v_and_b32_e32 v107, 0xffff0000, v219
	v_pk_add_f32 v[102:103], v[102:103], v[106:107]
	v_pk_add_f32 v[100:101], v[100:101], v[104:105]
	v_lshlrev_b32_e32 v104, 16, v220
	v_and_b32_e32 v105, 0xffff0000, v220
	v_lshlrev_b32_e32 v106, 16, v221
	v_and_b32_e32 v107, 0xffff0000, v221
	v_pk_add_f32 v[106:107], v[98:99], v[106:107]
	v_pk_add_f32 v[98:99], v[96:97], v[104:105]
	v_cvt_pk_bf16_f32 v96, v100, v101
	v_cvt_pk_bf16_f32 v97, v102, v103
	s_nop 0
	v_cvt_pk_bf16_f32 v98, v98, v99
	v_cvt_pk_bf16_f32 v99, v106, v107
	global_store_dwordx4 v[108:109], v[96:99], off offset:256
	s_nop 1
	s_waitcnt vmcnt(15)
	v_lshlrev_b32_e32 v96, 16, v222
	v_and_b32_e32 v97, 0xffff0000, v222
	v_lshlrev_b32_e32 v98, 16, v223
	v_and_b32_e32 v99, 0xffff0000, v223
	v_pk_add_f32 v[94:95], v[94:95], v[98:99]
	v_pk_add_f32 v[92:93], v[92:93], v[96:97]
	v_lshlrev_b32_e32 v96, 16, v224
	v_and_b32_e32 v97, 0xffff0000, v224
	v_lshlrev_b32_e32 v98, 16, v225
	v_and_b32_e32 v99, 0xffff0000, v225
	v_pk_add_f32 v[98:99], v[90:91], v[98:99]
	v_pk_add_f32 v[90:91], v[88:89], v[96:97]
	v_cvt_pk_bf16_f32 v88, v92, v93
	v_lshl_add_u64 v[92:93], s[52:53], 0, v[196:197]
	v_cvt_pk_bf16_f32 v89, v94, v95
	v_cvt_pk_bf16_f32 v90, v90, v91
	v_cvt_pk_bf16_f32 v91, v98, v99
	v_lshl_add_u64 v[92:93], v[92:93], 0, v[184:185]
	global_store_dwordx4 v[92:93], v[88:91], off
	s_nop 1
	s_waitcnt vmcnt(15)
; __device__ __forceinline__ unsigned cvt_pk_bf16(float lo, float hi) { unsigned r; asm volatile("v_cvt_pk_bf16_f32 %0, %1, %2" : "=v"(r) : "v"(lo), "v"(hi)); return r; }
;     __device__ __forceinline__ void operator()(const f32x4 (&acc)[2][2][4][2], const Unit& u, int wr, int wc, int fr, int fq) const {
;     ...
; #pragma unroll
;             for (int ai = 0; ai < 2; ++ai)
; #pragma unroll
;                 for (int m = 0; m < 4; ++m)
; #pragma unroll
;                     for (int bj = 0; bj < 2; ++bj) { const u32x4 b = bv[ai][m][bj];
;                         const f32x4 v0 = acc[ai][bj][m][0] + (f32x4){__builtin_bit_cast(float, b.x << 16), __builtin_bit_cast(float, b.x & 0xffff0000u), __builtin_bit_cast(float, b.y << 16), __builtin_bit_cast(float, b.y & 0xffff0000u)};
;                         const f32x4 v1 = acc[ai][bj][m][1] + (f32x4){__builtin_bit_cast(float, b.z << 16), __builtin_bit_cast(float, b.z & 0xffff0000u), __builtin_bit_cast(float, b.w << 16), __builtin_bit_cast(float, b.w & 0xffff0000u)};
;                         u32x4 w; w.x = cvt_pk_bf16(v0[0], v0[1]); w.y = cvt_pk_bf16(v0[2], v0[3]); w.z = cvt_pk_bf16(v1[0], v1[1]); w.w = cvt_pk_bf16(v1[2], v1[3]);
;                         *(u32x4*)(outb + (size_t)(row0 + ai * HALF + m * 16) * ldc + col0 + bj * HALF) = w; }
	v_lshlrev_b32_e32 v88, 16, v226
	v_and_b32_e32 v89, 0xffff0000, v226
	v_lshlrev_b32_e32 v90, 16, v227
	v_and_b32_e32 v91, 0xffff0000, v227
	v_pk_add_f32 v[86:87], v[86:87], v[90:91]
	v_pk_add_f32 v[84:85], v[84:85], v[88:89]
	v_lshlrev_b32_e32 v88, 16, v228
	v_and_b32_e32 v89, 0xffff0000, v228
	v_lshlrev_b32_e32 v90, 16, v229
	v_and_b32_e32 v91, 0xffff0000, v229
	v_pk_add_f32 v[90:91], v[82:83], v[90:91]
	v_pk_add_f32 v[82:83], v[80:81], v[88:89]
	v_cvt_pk_bf16_f32 v80, v84, v85
	v_cvt_pk_bf16_f32 v81, v86, v87
	s_nop 0
	v_cvt_pk_bf16_f32 v82, v82, v83
	v_cvt_pk_bf16_f32 v83, v90, v91
	global_store_dwordx4 v[92:93], v[80:83], off offset:256
	s_nop 1
	s_waitcnt vmcnt(15)
	v_lshlrev_b32_e32 v80, 16, v164
	v_and_b32_e32 v81, 0xffff0000, v164
	v_lshlrev_b32_e32 v82, 16, v165
	v_and_b32_e32 v83, 0xffff0000, v165
	v_pk_add_f32 v[78:79], v[78:79], v[82:83]
	v_pk_add_f32 v[76:77], v[76:77], v[80:81]
	v_lshlrev_b32_e32 v80, 16, v166
	v_and_b32_e32 v81, 0xffff0000, v166
	v_lshlrev_b32_e32 v82, 16, v167
	v_and_b32_e32 v83, 0xffff0000, v167
	v_pk_add_f32 v[82:83], v[74:75], v[82:83]
	v_pk_add_f32 v[74:75], v[72:73], v[80:81]
	v_cvt_pk_bf16_f32 v72, v76, v77
	v_lshl_add_u64 v[76:77], s[52:53], 0, v[194:195]
	v_cvt_pk_bf16_f32 v73, v78, v79
	v_cvt_pk_bf16_f32 v74, v74, v75
	v_cvt_pk_bf16_f32 v75, v82, v83
	v_lshl_add_u64 v[76:77], v[76:77], 0, v[184:185]
	global_store_dwordx4 v[76:77], v[72:75], off
	s_nop 1
	s_waitcnt vmcnt(15)
	v_lshlrev_b32_e32 v72, 16, v160
	v_and_b32_e32 v73, 0xffff0000, v160
	v_lshlrev_b32_e32 v74, 16, v161
	v_and_b32_e32 v75, 0xffff0000, v161
	v_pk_add_f32 v[70:71], v[70:71], v[74:75]
	v_pk_add_f32 v[68:69], v[68:69], v[72:73]
	v_lshlrev_b32_e32 v72, 16, v162
	v_and_b32_e32 v73, 0xffff0000, v162
	v_lshlrev_b32_e32 v74, 16, v163
	v_and_b32_e32 v75, 0xffff0000, v163
	v_pk_add_f32 v[74:75], v[66:67], v[74:75]
	v_pk_add_f32 v[66:67], v[64:65], v[72:73]
	v_cvt_pk_bf16_f32 v64, v68, v69
	v_cvt_pk_bf16_f32 v65, v70, v71
	s_nop 0
	v_cvt_pk_bf16_f32 v66, v66, v67
	v_cvt_pk_bf16_f32 v67, v74, v75
	global_store_dwordx4 v[76:77], v[64:67], off offset:256
	s_nop 1
	s_waitcnt vmcnt(15)
	v_lshlrev_b32_e32 v64, 16, v156
	v_and_b32_e32 v65, 0xffff0000, v156
	v_lshlrev_b32_e32 v66, 16, v157
	v_and_b32_e32 v67, 0xffff0000, v157
	v_pk_add_f32 v[62:63], v[62:63], v[66:67]
	v_pk_add_f32 v[60:61], v[60:61], v[64:65]
	v_lshlrev_b32_e32 v64, 16, v158
	v_and_b32_e32 v65, 0xffff0000, v158
	v_lshlrev_b32_e32 v66, 16, v159
	v_and_b32_e32 v67, 0xffff0000, v159
	v_pk_add_f32 v[66:67], v[58:59], v[66:67]
	v_pk_add_f32 v[58:59], v[56:57], v[64:65]
	v_cvt_pk_bf16_f32 v56, v60, v61
	v_lshl_add_u64 v[60:61], s[52:53], 0, v[192:193]
	v_cvt_pk_bf16_f32 v57, v62, v63
	v_cvt_pk_bf16_f32 v58, v58, v59
	v_cvt_pk_bf16_f32 v59, v66, v67
	v_lshl_add_u64 v[60:61], v[60:61], 0, v[184:185]
	global_store_dwordx4 v[60:61], v[56:59], off
	s_nop 1
	s_waitcnt vmcnt(15)
	v_lshlrev_b32_e32 v56, 16, v152
	v_and_b32_e32 v57, 0xffff0000, v152
	v_lshlrev_b32_e32 v58, 16, v153
	v_and_b32_e32 v59, 0xffff0000, v153
	v_pk_add_f32 v[54:55], v[54:55], v[58:59]
	v_pk_add_f32 v[52:53], v[52:53], v[56:57]
	v_lshlrev_b32_e32 v56, 16, v154
	v_and_b32_e32 v57, 0xffff0000, v154
	v_lshlrev_b32_e32 v58, 16, v155
	v_and_b32_e32 v59, 0xffff0000, v155
	v_pk_add_f32 v[58:59], v[50:51], v[58:59]
	v_pk_add_f32 v[50:51], v[48:49], v[56:57]
	v_cvt_pk_bf16_f32 v48, v52, v53
	v_cvt_pk_bf16_f32 v49, v54, v55
	s_nop 0
	v_cvt_pk_bf16_f32 v50, v50, v51
	v_cvt_pk_bf16_f32 v51, v58, v59
	global_store_dwordx4 v[60:61], v[48:51], off offset:256
	s_nop 1
	s_waitcnt vmcnt(15)
	v_lshlrev_b32_e32 v48, 16, v148
	v_and_b32_e32 v49, 0xffff0000, v148
	v_lshlrev_b32_e32 v50, 16, v149
	v_and_b32_e32 v51, 0xffff0000, v149
	v_pk_add_f32 v[46:47], v[46:47], v[50:51]
	v_pk_add_f32 v[44:45], v[44:45], v[48:49]
	v_lshlrev_b32_e32 v48, 16, v150
	v_and_b32_e32 v49, 0xffff0000, v150
	v_lshlrev_b32_e32 v50, 16, v151
	v_and_b32_e32 v51, 0xffff0000, v151
	v_pk_add_f32 v[50:51], v[42:43], v[50:51]
	v_pk_add_f32 v[42:43], v[40:41], v[48:49]
	v_cvt_pk_bf16_f32 v40, v44, v45
	v_lshl_add_u64 v[44:45], s[52:53], 0, v[190:191]
	v_cvt_pk_bf16_f32 v41, v46, v47
	v_cvt_pk_bf16_f32 v42, v42, v43
	v_cvt_pk_bf16_f32 v43, v50, v51
	v_lshl_add_u64 v[44:45], v[44:45], 0, v[184:185]
	global_store_dwordx4 v[44:45], v[40:43], off
	s_nop 1
	s_waitcnt vmcnt(15)
; __device__ __forceinline__ unsigned cvt_pk_bf16(float lo, float hi) { unsigned r; asm volatile("v_cvt_pk_bf16_f32 %0, %1, %2" : "=v"(r) : "v"(lo), "v"(hi)); return r; }
;     __device__ __forceinline__ void operator()(const f32x4 (&acc)[2][2][4][2], const Unit& u, int wr, int wc, int fr, int fq) const {
;     ...
; #pragma unroll
;             for (int ai = 0; ai < 2; ++ai)
; #pragma unroll
;                 for (int m = 0; m < 4; ++m)
; #pragma unroll
;                     for (int bj = 0; bj < 2; ++bj) { const u32x4 b = bv[ai][m][bj];
;                         const f32x4 v0 = acc[ai][bj][m][0] + (f32x4){__builtin_bit_cast(float, b.x << 16), __builtin_bit_cast(float, b.x & 0xffff0000u), __builtin_bit_cast(float, b.y << 16), __builtin_bit_cast(float, b.y & 0xffff0000u)};
;                         const f32x4 v1 = acc[ai][bj][m][1] + (f32x4){__builtin_bit_cast(float, b.z << 16), __builtin_bit_cast(float, b.z & 0xffff0000u), __builtin_bit_cast(float, b.w << 16), __builtin_bit_cast(float, b.w & 0xffff0000u)};
;                         u32x4 w; w.x = cvt_pk_bf16(v0[0], v0[1]); w.y = cvt_pk_bf16(v0[2], v0[3]); w.z = cvt_pk_bf16(v1[0], v1[1]); w.w = cvt_pk_bf16(v1[2], v1[3]);
;                         *(u32x4*)(outb + (size_t)(row0 + ai * HALF + m * 16) * ldc + col0 + bj * HALF) = w; }
	v_lshlrev_b32_e32 v40, 16, v144
	v_and_b32_e32 v41, 0xffff0000, v144
	v_lshlrev_b32_e32 v42, 16, v145
	v_and_b32_e32 v43, 0xffff0000, v145
	v_pk_add_f32 v[38:39], v[38:39], v[42:43]
	v_pk_add_f32 v[36:37], v[36:37], v[40:41]
	v_lshlrev_b32_e32 v40, 16, v146
	v_and_b32_e32 v41, 0xffff0000, v146
	v_lshlrev_b32_e32 v42, 16, v147
	v_and_b32_e32 v43, 0xffff0000, v147
	v_pk_add_f32 v[42:43], v[34:35], v[42:43]
	v_pk_add_f32 v[34:35], v[32:33], v[40:41]
	v_cvt_pk_bf16_f32 v32, v36, v37
	v_cvt_pk_bf16_f32 v33, v38, v39
	s_nop 0
	v_cvt_pk_bf16_f32 v34, v34, v35
	v_cvt_pk_bf16_f32 v35, v42, v43
	global_store_dwordx4 v[44:45], v[32:35], off offset:256
	s_nop 1
	s_waitcnt vmcnt(15)
	v_lshlrev_b32_e32 v32, 16, v140
	v_and_b32_e32 v33, 0xffff0000, v140
	v_lshlrev_b32_e32 v34, 16, v141
	v_and_b32_e32 v35, 0xffff0000, v141
	v_pk_add_f32 v[30:31], v[30:31], v[34:35]
	v_pk_add_f32 v[28:29], v[28:29], v[32:33]
	v_lshlrev_b32_e32 v32, 16, v142
	v_and_b32_e32 v33, 0xffff0000, v142
	v_lshlrev_b32_e32 v34, 16, v143
	v_and_b32_e32 v35, 0xffff0000, v143
	v_pk_add_f32 v[34:35], v[26:27], v[34:35]
	v_pk_add_f32 v[26:27], v[24:25], v[32:33]
	v_cvt_pk_bf16_f32 v24, v28, v29
	v_lshl_add_u64 v[28:29], s[52:53], 0, v[188:189]
	v_cvt_pk_bf16_f32 v25, v30, v31
	v_cvt_pk_bf16_f32 v26, v26, v27
	v_cvt_pk_bf16_f32 v27, v34, v35
	v_lshl_add_u64 v[28:29], v[28:29], 0, v[184:185]
	global_store_dwordx4 v[28:29], v[24:27], off
	s_nop 1
	s_waitcnt vmcnt(15)
	v_lshlrev_b32_e32 v24, 16, v136
	v_and_b32_e32 v25, 0xffff0000, v136
	v_lshlrev_b32_e32 v26, 16, v137
	v_and_b32_e32 v27, 0xffff0000, v137
	v_pk_add_f32 v[22:23], v[22:23], v[26:27]
	v_pk_add_f32 v[20:21], v[20:21], v[24:25]
	v_lshlrev_b32_e32 v24, 16, v138
	v_and_b32_e32 v25, 0xffff0000, v138
	v_lshlrev_b32_e32 v26, 16, v139
	v_and_b32_e32 v27, 0xffff0000, v139
	v_pk_add_f32 v[26:27], v[18:19], v[26:27]
	v_pk_add_f32 v[18:19], v[16:17], v[24:25]
	v_cvt_pk_bf16_f32 v16, v20, v21
	v_cvt_pk_bf16_f32 v17, v22, v23
	s_nop 0
	v_cvt_pk_bf16_f32 v18, v18, v19
	v_cvt_pk_bf16_f32 v19, v26, v27
	global_store_dwordx4 v[28:29], v[16:19], off offset:256
	s_nop 1
	s_waitcnt vmcnt(15)
	v_lshlrev_b32_e32 v16, 16, v132
	v_and_b32_e32 v17, 0xffff0000, v132
	v_lshlrev_b32_e32 v18, 16, v133
	v_and_b32_e32 v19, 0xffff0000, v133
	v_pk_add_f32 v[14:15], v[14:15], v[18:19]
	v_pk_add_f32 v[12:13], v[12:13], v[16:17]
	v_lshlrev_b32_e32 v16, 16, v134
	v_and_b32_e32 v17, 0xffff0000, v134
	v_lshlrev_b32_e32 v18, 16, v135
	v_and_b32_e32 v19, 0xffff0000, v135
	v_pk_add_f32 v[18:19], v[10:11], v[18:19]
	v_pk_add_f32 v[10:11], v[8:9], v[16:17]
	v_cvt_pk_bf16_f32 v8, v12, v13
	v_lshl_add_u64 v[12:13], s[52:53], 0, v[186:187]
	v_cvt_pk_bf16_f32 v9, v14, v15
	v_cvt_pk_bf16_f32 v10, v10, v11
	v_cvt_pk_bf16_f32 v11, v18, v19
	v_lshl_add_u64 v[12:13], v[12:13], 0, v[184:185]
	global_store_dwordx4 v[12:13], v[8:11], off
	s_nop 1
	s_waitcnt vmcnt(15)
	v_lshlrev_b32_e32 v8, 16, v128
	v_and_b32_e32 v9, 0xffff0000, v128
	v_lshlrev_b32_e32 v10, 16, v129
	v_and_b32_e32 v11, 0xffff0000, v129
	v_pk_add_f32 v[6:7], v[6:7], v[10:11]
	v_pk_add_f32 v[4:5], v[4:5], v[8:9]
	v_lshlrev_b32_e32 v8, 16, v130
	v_and_b32_e32 v9, 0xffff0000, v130
	v_lshlrev_b32_e32 v10, 16, v131
	v_and_b32_e32 v11, 0xffff0000, v131
	v_pk_add_f32 v[10:11], v[2:3], v[10:11]
	v_pk_add_f32 v[2:3], v[0:1], v[8:9]
	v_cvt_pk_bf16_f32 v0, v4, v5
	v_cvt_pk_bf16_f32 v1, v6, v7
	s_nop 0
	v_cvt_pk_bf16_f32 v2, v2, v3
	v_cvt_pk_bf16_f32 v3, v10, v11
	global_store_dwordx4 v[12:13], v[0:3], off offset:256
	s_cbranch_vccnz .LBB0_1045
	s_andn2_b64 vcc, exec, s[10:11]
	s_cbranch_vccnz .LBB0_1044
	s_barrier
	s_branch .LBB0_1044

; __device__ __forceinline__ unsigned cvt_pk_bf16(float lo, float hi) { unsigned r; asm volatile("v_cvt_pk_bf16_f32 %0, %1, %2" : "=v"(r) : "v"(lo), "v"(hi)); return r; }
;     __device__ __forceinline__ void operator()(const f32x4 (&acc)[2][2][4][2], const Unit& u, int wr, int wc, int fr, int fq) const {
;     ...
;             u32x4 bv[2][4][2];
; #pragma unroll
;             for (int ai = 0; ai < 2; ++ai)
; #pragma unroll
;                 for (int m = 0; m < 4; ++m)
; #pragma unroll
;                     for (int bj = 0; bj < 2; ++bj) bv[ai][m][bj] = *(const u32x4*)(baseb + (size_t)(row0 + ai * HALF + m * 16) * ldc + col0 + bj * HALF);
;             asm volatile("" ::: "memory");
; #pragma unroll
;             for (int ai = 0; ai < 2; ++ai)
; #pragma unroll
;                 for (int m = 0; m < 4; ++m)
; #pragma unroll
;                     for (int bj = 0; bj < 2; ++bj) { const u32x4 b = bv[ai][m][bj];
;                         const f32x4 v0 = acc[ai][bj][m][0] + (f32x4){__builtin_bit_cast(float, b.x << 16), __builtin_bit_cast(float, b.x & 0xffff0000u), __builtin_bit_cast(float, b.y << 16), __builtin_bit_cast(float, b.y & 0xffff0000u)};
;                         const f32x4 v1 = acc[ai][bj][m][1] + (f32x4){__builtin_bit_cast(float, b.z << 16), __builtin_bit_cast(float, b.z & 0xffff0000u), __builtin_bit_cast(float, b.w << 16), __builtin_bit_cast(float, b.w & 0xffff0000u)};
;                         u32x4 w; w.x = cvt_pk_bf16(v0[0], v0[1]); w.y = cvt_pk_bf16(v0[2], v0[3]); w.z = cvt_pk_bf16(v1[0], v1[1]); w.w = cvt_pk_bf16(v1[2], v1[3]);
;                         *(u32x4*)(outb + (size_t)(row0 + ai * HALF + m * 16) * ldc + col0 + bj * HALF) = w; }
.LBB0_1263:
	v_lshl_or_b32 v130, s24, 8, v201
	v_lshl_add_u32 v128, s48, 8, v199
	v_ashrrev_i32_e32 v131, 31, v130
	v_lshlrev_b64 v[184:185], 1, v[130:131]
	v_ashrrev_i32_e32 v129, 31, v128
	v_lshl_add_u64 v[130:131], s[52:53], 0, v[184:185]
	v_lshlrev_b64 v[132:133], 12, v[128:129]
	v_lshl_add_u64 v[134:135], v[130:131], 0, v[132:133]
	global_load_dwordx4 v[206:209], v[134:135], off
	global_load_dwordx4 v[210:213], v[134:135], off offset:256
	v_or_b32_e32 v134, 16, v128
	v_ashrrev_i32_e32 v135, 31, v134
	v_lshlrev_b64 v[230:231], 12, v[134:135]
	v_lshl_add_u64 v[134:135], v[130:131], 0, v[230:231]
	global_load_dwordx4 v[214:217], v[134:135], off
	global_load_dwordx4 v[218:221], v[134:135], off offset:256
	v_or_b32_e32 v136, 32, v128
	v_or_b32_e32 v128, 48, v128
	v_ashrrev_i32_e32 v137, 31, v136
	v_ashrrev_i32_e32 v129, 31, v128
	v_lshlrev_b64 v[196:197], 12, v[136:137]
	v_lshlrev_b64 v[194:195], 12, v[128:129]
	v_lshl_add_u64 v[192:193], v[132:133], 0, s[16:17]
	v_lshl_add_u64 v[190:191], v[132:133], 0, s[18:19]
	v_lshl_add_u64 v[188:189], v[132:133], 0, s[20:21]
	v_lshl_add_u64 v[186:187], v[132:133], 0, s[22:23]
	v_lshl_add_u64 v[128:129], s[28:29], 0, v[132:133]
	v_lshl_add_u64 v[132:133], v[130:131], 0, v[196:197]
	v_lshl_add_u64 v[134:135], v[130:131], 0, v[194:195]
	v_lshl_add_u64 v[136:137], v[130:131], 0, v[192:193]
	v_lshl_add_u64 v[138:139], v[130:131], 0, v[190:191]
	v_lshl_add_u64 v[232:233], v[130:131], 0, v[188:189]
	v_lshl_add_u64 v[130:131], v[130:131], 0, v[186:187]
	v_lshl_add_u64 v[234:235], v[128:129], 0, v[184:185]
	global_load_dwordx4 v[222:225], v[132:133], off
	global_load_dwordx4 v[226:229], v[132:133], off offset:256
	global_load_dwordx4 v[164:167], v[134:135], off
	global_load_dwordx4 v[160:163], v[134:135], off offset:256
	global_load_dwordx4 v[156:159], v[136:137], off
	global_load_dwordx4 v[152:155], v[136:137], off offset:256
	global_load_dwordx4 v[148:151], v[138:139], off
	global_load_dwordx4 v[144:147], v[138:139], off offset:256
	global_load_dwordx4 v[140:143], v[232:233], off
	s_nop 0
	global_load_dwordx4 v[136:139], v[232:233], off offset:256
	global_load_dwordx4 v[132:135], v[130:131], off
	s_nop 0
	global_load_dwordx4 v[128:131], v[130:131], off offset:256
	s_andn2_b64 vcc, exec, s[6:7]
	s_mov_b64 s[6:7], -1
	s_waitcnt vmcnt(15)
	v_lshlrev_b32_e32 v232, 16, v206
	v_and_b32_e32 v233, 0xffff0000, v206
	v_lshlrev_b32_e32 v206, 16, v207
	v_and_b32_e32 v207, 0xffff0000, v207
	v_lshlrev_b32_e32 v236, 16, v208
	v_and_b32_e32 v237, 0xffff0000, v208
	v_lshlrev_b32_e32 v208, 16, v209
	v_and_b32_e32 v209, 0xffff0000, v209
	s_waitcnt vmcnt(14)
	v_lshlrev_b32_e32 v240, 16, v212
	v_and_b32_e32 v241, 0xffff0000, v212
	v_lshlrev_b32_e32 v212, 16, v213
	v_and_b32_e32 v213, 0xffff0000, v213
	v_lshlrev_b32_e32 v238, 16, v210
	v_and_b32_e32 v239, 0xffff0000, v210
	v_lshlrev_b32_e32 v210, 16, v211
	v_and_b32_e32 v211, 0xffff0000, v211
	v_pk_add_f32 v[126:127], v[126:127], v[206:207]
	v_pk_add_f32 v[124:125], v[124:125], v[232:233]
	v_pk_add_f32 v[122:123], v[122:123], v[208:209]
	v_pk_add_f32 v[120:121], v[120:121], v[236:237]
	v_pk_add_f32 v[206:207], v[106:107], v[212:213]
	v_pk_add_f32 v[208:209], v[104:105], v[240:241]
	v_cvt_pk_bf16_f32 v104, v124, v125
	v_cvt_pk_bf16_f32 v105, v126, v127
	v_cvt_pk_bf16_f32 v106, v120, v121
	v_cvt_pk_bf16_f32 v107, v122, v123
	s_waitcnt vmcnt(13)
	v_lshlrev_b32_e32 v244, 16, v216
	v_and_b32_e32 v245, 0xffff0000, v216
	v_pk_add_f32 v[114:115], v[114:115], v[210:211]
	v_pk_add_f32 v[112:113], v[112:113], v[238:239]
	global_store_dwordx4 v[234:235], v[104:107], off
	v_lshlrev_b32_e32 v242, 16, v214
	v_and_b32_e32 v243, 0xffff0000, v214
	v_cvt_pk_bf16_f32 v104, v112, v113
	v_cvt_pk_bf16_f32 v105, v114, v115
	v_cvt_pk_bf16_f32 v106, v208, v209
	v_cvt_pk_bf16_f32 v107, v206, v207
	v_lshlrev_b32_e32 v214, 16, v215
	v_and_b32_e32 v215, 0xffff0000, v215
	v_lshlrev_b32_e32 v216, 16, v217
	global_store_dwordx4 v[234:235], v[104:107], off offset:256
	v_and_b32_e32 v217, 0xffff0000, v217
	v_pk_add_f32 v[118:119], v[118:119], v[214:215]
	v_pk_add_f32 v[106:107], v[108:109], v[244:245]
	v_lshl_add_u64 v[108:109], s[28:29], 0, v[230:231]
	v_pk_add_f32 v[116:117], v[116:117], v[242:243]
	v_pk_add_f32 v[110:111], v[110:111], v[216:217]
	v_cvt_pk_bf16_f32 v104, v116, v117
	v_cvt_pk_bf16_f32 v105, v118, v119
	v_cvt_pk_bf16_f32 v106, v106, v107
	v_lshl_add_u64 v[108:109], v[108:109], 0, v[184:185]
	v_cvt_pk_bf16_f32 v107, v110, v111
	global_store_dwordx4 v[108:109], v[104:107], off
	s_nop 1
	s_waitcnt vmcnt(15)
	v_lshlrev_b32_e32 v104, 16, v218
	v_and_b32_e32 v105, 0xffff0000, v218
	v_lshlrev_b32_e32 v106, 16, v219
	v_and_b32_e32 v107, 0xffff0000, v219
	v_pk_add_f32 v[102:103], v[102:103], v[106:107]
	v_pk_add_f32 v[100:101], v[100:101], v[104:105]
	v_lshlrev_b32_e32 v104, 16, v220
	v_and_b32_e32 v105, 0xffff0000, v220
	v_lshlrev_b32_e32 v106, 16, v221
	v_and_b32_e32 v107, 0xffff0000, v221
	v_pk_add_f32 v[106:107], v[98:99], v[106:107]
	v_pk_add_f32 v[98:99], v[96:97], v[104:105]
	v_cvt_pk_bf16_f32 v96, v100, v101
	v_cvt_pk_bf16_f32 v97, v102, v103
	s_nop 0
	v_cvt_pk_bf16_f32 v98, v98, v99
	v_cvt_pk_bf16_f32 v99, v106, v107
	global_store_dwordx4 v[108:109], v[96:99], off offset:256
	s_nop 1
	s_waitcnt vmcnt(15)
	v_lshlrev_b32_e32 v96, 16, v222
	v_and_b32_e32 v97, 0xffff0000, v222
	v_lshlrev_b32_e32 v98, 16, v223
	v_and_b32_e32 v99, 0xffff0000, v223
	v_pk_add_f32 v[94:95], v[94:95], v[98:99]
	v_pk_add_f32 v[92:93], v[92:93], v[96:97]
	v_lshlrev_b32_e32 v96, 16, v224
	v_and_b32_e32 v97, 0xffff0000, v224
	v_lshlrev_b32_e32 v98, 16, v225
	v_and_b32_e32 v99, 0xffff0000, v225
	v_pk_add_f32 v[98:99], v[90:91], v[98:99]
	v_pk_add_f32 v[90:91], v[88:89], v[96:97]
	v_cvt_pk_bf16_f32 v88, v92, v93
	v_lshl_add_u64 v[92:93], s[28:29], 0, v[196:197]
	v_cvt_pk_bf16_f32 v89, v94, v95
	v_cvt_pk_bf16_f32 v90, v90, v91
	v_cvt_pk_bf16_f32 v91, v98, v99
	v_lshl_add_u64 v[92:93], v[92:93], 0, v[184:185]
	global_store_dwordx4 v[92:93], v[88:91], off
	s_nop 1
	s_waitcnt vmcnt(15)
; __device__ __forceinline__ unsigned cvt_pk_bf16(float lo, float hi) { unsigned r; asm volatile("v_cvt_pk_bf16_f32 %0, %1, %2" : "=v"(r) : "v"(lo), "v"(hi)); return r; }
;     __device__ __forceinline__ void operator()(const f32x4 (&acc)[2][2][4][2], const Unit& u, int wr, int wc, int fr, int fq) const {
;     ...
; #pragma unroll
;             for (int ai = 0; ai < 2; ++ai)
; #pragma unroll
;                 for (int m = 0; m < 4; ++m)
; #pragma unroll
;                     for (int bj = 0; bj < 2; ++bj) { const u32x4 b = bv[ai][m][bj];
;                         const f32x4 v0 = acc[ai][bj][m][0] + (f32x4){__builtin_bit_cast(float, b.x << 16), __builtin_bit_cast(float, b.x & 0xffff0000u), __builtin_bit_cast(float, b.y << 16), __builtin_bit_cast(float, b.y & 0xffff0000u)};
;                         const f32x4 v1 = acc[ai][bj][m][1] + (f32x4){__builtin_bit_cast(float, b.z << 16), __builtin_bit_cast(float, b.z & 0xffff0000u), __builtin_bit_cast(float, b.w << 16), __builtin_bit_cast(float, b.w & 0xffff0000u)};
;                         u32x4 w; w.x = cvt_pk_bf16(v0[0], v0[1]); w.y = cvt_pk_bf16(v0[2], v0[3]); w.z = cvt_pk_bf16(v1[0], v1[1]); w.w = cvt_pk_bf16(v1[2], v1[3]);
;                         *(u32x4*)(outb + (size_t)(row0 + ai * HALF + m * 16) * ldc + col0 + bj * HALF) = w; }
	v_lshlrev_b32_e32 v88, 16, v226
	v_and_b32_e32 v89, 0xffff0000, v226
	v_lshlrev_b32_e32 v90, 16, v227
	v_and_b32_e32 v91, 0xffff0000, v227
	v_pk_add_f32 v[86:87], v[86:87], v[90:91]
	v_pk_add_f32 v[84:85], v[84:85], v[88:89]
	v_lshlrev_b32_e32 v88, 16, v228
	v_and_b32_e32 v89, 0xffff0000, v228
	v_lshlrev_b32_e32 v90, 16, v229
	v_and_b32_e32 v91, 0xffff0000, v229
	v_pk_add_f32 v[90:91], v[82:83], v[90:91]
	v_pk_add_f32 v[82:83], v[80:81], v[88:89]
	v_cvt_pk_bf16_f32 v80, v84, v85
	v_cvt_pk_bf16_f32 v81, v86, v87
	s_nop 0
	v_cvt_pk_bf16_f32 v82, v82, v83
	v_cvt_pk_bf16_f32 v83, v90, v91
	global_store_dwordx4 v[92:93], v[80:83], off offset:256
	s_nop 1
	s_waitcnt vmcnt(15)
	v_lshlrev_b32_e32 v80, 16, v164
	v_and_b32_e32 v81, 0xffff0000, v164
	v_lshlrev_b32_e32 v82, 16, v165
	v_and_b32_e32 v83, 0xffff0000, v165
	v_pk_add_f32 v[78:79], v[78:79], v[82:83]
	v_pk_add_f32 v[76:77], v[76:77], v[80:81]
	v_lshlrev_b32_e32 v80, 16, v166
	v_and_b32_e32 v81, 0xffff0000, v166
	v_lshlrev_b32_e32 v82, 16, v167
	v_and_b32_e32 v83, 0xffff0000, v167
	v_pk_add_f32 v[82:83], v[74:75], v[82:83]
	v_pk_add_f32 v[74:75], v[72:73], v[80:81]
	v_cvt_pk_bf16_f32 v72, v76, v77
	v_lshl_add_u64 v[76:77], s[28:29], 0, v[194:195]
	v_cvt_pk_bf16_f32 v73, v78, v79
	v_cvt_pk_bf16_f32 v74, v74, v75
	v_cvt_pk_bf16_f32 v75, v82, v83
	v_lshl_add_u64 v[76:77], v[76:77], 0, v[184:185]
	global_store_dwordx4 v[76:77], v[72:75], off
	s_nop 1
	s_waitcnt vmcnt(15)
	v_lshlrev_b32_e32 v72, 16, v160
	v_and_b32_e32 v73, 0xffff0000, v160
	v_lshlrev_b32_e32 v74, 16, v161
	v_and_b32_e32 v75, 0xffff0000, v161
	v_pk_add_f32 v[70:71], v[70:71], v[74:75]
	v_pk_add_f32 v[68:69], v[68:69], v[72:73]
	v_lshlrev_b32_e32 v72, 16, v162
	v_and_b32_e32 v73, 0xffff0000, v162
	v_lshlrev_b32_e32 v74, 16, v163
	v_and_b32_e32 v75, 0xffff0000, v163
	v_pk_add_f32 v[74:75], v[66:67], v[74:75]
	v_pk_add_f32 v[66:67], v[64:65], v[72:73]
	v_cvt_pk_bf16_f32 v64, v68, v69
	v_cvt_pk_bf16_f32 v65, v70, v71
	s_nop 0
	v_cvt_pk_bf16_f32 v66, v66, v67
	v_cvt_pk_bf16_f32 v67, v74, v75
	global_store_dwordx4 v[76:77], v[64:67], off offset:256
	s_nop 1
	s_waitcnt vmcnt(15)
	v_lshlrev_b32_e32 v64, 16, v156
	v_and_b32_e32 v65, 0xffff0000, v156
	v_lshlrev_b32_e32 v66, 16, v157
	v_and_b32_e32 v67, 0xffff0000, v157
	v_pk_add_f32 v[62:63], v[62:63], v[66:67]
	v_pk_add_f32 v[60:61], v[60:61], v[64:65]
	v_lshlrev_b32_e32 v64, 16, v158
	v_and_b32_e32 v65, 0xffff0000, v158
	v_lshlrev_b32_e32 v66, 16, v159
	v_and_b32_e32 v67, 0xffff0000, v159
	v_pk_add_f32 v[66:67], v[58:59], v[66:67]
	v_pk_add_f32 v[58:59], v[56:57], v[64:65]
	v_cvt_pk_bf16_f32 v56, v60, v61
	v_lshl_add_u64 v[60:61], s[28:29], 0, v[192:193]
	v_cvt_pk_bf16_f32 v57, v62, v63
	v_cvt_pk_bf16_f32 v58, v58, v59
	v_cvt_pk_bf16_f32 v59, v66, v67
	v_lshl_add_u64 v[60:61], v[60:61], 0, v[184:185]
	global_store_dwordx4 v[60:61], v[56:59], off
	s_nop 1
	s_waitcnt vmcnt(15)
	v_lshlrev_b32_e32 v56, 16, v152
	v_and_b32_e32 v57, 0xffff0000, v152
	v_lshlrev_b32_e32 v58, 16, v153
	v_and_b32_e32 v59, 0xffff0000, v153
	v_pk_add_f32 v[54:55], v[54:55], v[58:59]
	v_pk_add_f32 v[52:53], v[52:53], v[56:57]
	v_lshlrev_b32_e32 v56, 16, v154
	v_and_b32_e32 v57, 0xffff0000, v154
	v_lshlrev_b32_e32 v58, 16, v155
	v_and_b32_e32 v59, 0xffff0000, v155
	v_pk_add_f32 v[58:59], v[50:51], v[58:59]
	v_pk_add_f32 v[50:51], v[48:49], v[56:57]
	v_cvt_pk_bf16_f32 v48, v52, v53
	v_cvt_pk_bf16_f32 v49, v54, v55
	s_nop 0
	v_cvt_pk_bf16_f32 v50, v50, v51
	v_cvt_pk_bf16_f32 v51, v58, v59
	global_store_dwordx4 v[60:61], v[48:51], off offset:256
	s_nop 1
	s_waitcnt vmcnt(15)
	v_lshlrev_b32_e32 v48, 16, v148
	v_and_b32_e32 v49, 0xffff0000, v148
	v_lshlrev_b32_e32 v50, 16, v149
	v_and_b32_e32 v51, 0xffff0000, v149
	v_pk_add_f32 v[46:47], v[46:47], v[50:51]
	v_pk_add_f32 v[44:45], v[44:45], v[48:49]
	v_lshlrev_b32_e32 v48, 16, v150
	v_and_b32_e32 v49, 0xffff0000, v150
	v_lshlrev_b32_e32 v50, 16, v151
	v_and_b32_e32 v51, 0xffff0000, v151
	v_pk_add_f32 v[50:51], v[42:43], v[50:51]
	v_pk_add_f32 v[42:43], v[40:41], v[48:49]
	v_cvt_pk_bf16_f32 v40, v44, v45
	v_lshl_add_u64 v[44:45], s[28:29], 0, v[190:191]
	v_cvt_pk_bf16_f32 v41, v46, v47
	v_cvt_pk_bf16_f32 v42, v42, v43
	v_cvt_pk_bf16_f32 v43, v50, v51
	v_lshl_add_u64 v[44:45], v[44:45], 0, v[184:185]
	global_store_dwordx4 v[44:45], v[40:43], off
	s_nop 1
	s_waitcnt vmcnt(15)
; __device__ __forceinline__ unsigned cvt_pk_bf16(float lo, float hi) { unsigned r; asm volatile("v_cvt_pk_bf16_f32 %0, %1, %2" : "=v"(r) : "v"(lo), "v"(hi)); return r; }
;     __device__ __forceinline__ void operator()(const f32x4 (&acc)[2][2][4][2], const Unit& u, int wr, int wc, int fr, int fq) const {
;     ...
; #pragma unroll
;             for (int ai = 0; ai < 2; ++ai)
; #pragma unroll
;                 for (int m = 0; m < 4; ++m)
; #pragma unroll
;                     for (int bj = 0; bj < 2; ++bj) { const u32x4 b = bv[ai][m][bj];
;                         const f32x4 v0 = acc[ai][bj][m][0] + (f32x4){__builtin_bit_cast(float, b.x << 16), __builtin_bit_cast(float, b.x & 0xffff0000u), __builtin_bit_cast(float, b.y << 16), __builtin_bit_cast(float, b.y & 0xffff0000u)};
;                         const f32x4 v1 = acc[ai][bj][m][1] + (f32x4){__builtin_bit_cast(float, b.z << 16), __builtin_bit_cast(float, b.z & 0xffff0000u), __builtin_bit_cast(float, b.w << 16), __builtin_bit_cast(float, b.w & 0xffff0000u)};
;                         u32x4 w; w.x = cvt_pk_bf16(v0[0], v0[1]); w.y = cvt_pk_bf16(v0[2], v0[3]); w.z = cvt_pk_bf16(v1[0], v1[1]); w.w = cvt_pk_bf16(v1[2], v1[3]);
;                         *(u32x4*)(outb + (size_t)(row0 + ai * HALF + m * 16) * ldc + col0 + bj * HALF) = w; }
	v_lshlrev_b32_e32 v40, 16, v144
	v_and_b32_e32 v41, 0xffff0000, v144
	v_lshlrev_b32_e32 v42, 16, v145
	v_and_b32_e32 v43, 0xffff0000, v145
	v_pk_add_f32 v[38:39], v[38:39], v[42:43]
	v_pk_add_f32 v[36:37], v[36:37], v[40:41]
	v_lshlrev_b32_e32 v40, 16, v146
	v_and_b32_e32 v41, 0xffff0000, v146
	v_lshlrev_b32_e32 v42, 16, v147
	v_and_b32_e32 v43, 0xffff0000, v147
	v_pk_add_f32 v[42:43], v[34:35], v[42:43]
	v_pk_add_f32 v[34:35], v[32:33], v[40:41]
	v_cvt_pk_bf16_f32 v32, v36, v37
	v_cvt_pk_bf16_f32 v33, v38, v39
	s_nop 0
	v_cvt_pk_bf16_f32 v34, v34, v35
	v_cvt_pk_bf16_f32 v35, v42, v43
	global_store_dwordx4 v[44:45], v[32:35], off offset:256
	s_nop 1
	s_waitcnt vmcnt(15)
	v_lshlrev_b32_e32 v32, 16, v140
	v_and_b32_e32 v33, 0xffff0000, v140
	v_lshlrev_b32_e32 v34, 16, v141
	v_and_b32_e32 v35, 0xffff0000, v141
	v_pk_add_f32 v[30:31], v[30:31], v[34:35]
	v_pk_add_f32 v[28:29], v[28:29], v[32:33]
	v_lshlrev_b32_e32 v32, 16, v142
	v_and_b32_e32 v33, 0xffff0000, v142
	v_lshlrev_b32_e32 v34, 16, v143
	v_and_b32_e32 v35, 0xffff0000, v143
	v_pk_add_f32 v[34:35], v[26:27], v[34:35]
	v_pk_add_f32 v[26:27], v[24:25], v[32:33]
	v_cvt_pk_bf16_f32 v24, v28, v29
	v_lshl_add_u64 v[28:29], s[28:29], 0, v[188:189]
	v_cvt_pk_bf16_f32 v25, v30, v31
	v_cvt_pk_bf16_f32 v26, v26, v27
	v_cvt_pk_bf16_f32 v27, v34, v35
	v_lshl_add_u64 v[28:29], v[28:29], 0, v[184:185]
	global_store_dwordx4 v[28:29], v[24:27], off
	s_nop 1
	s_waitcnt vmcnt(15)
	v_lshlrev_b32_e32 v24, 16, v136
	v_and_b32_e32 v25, 0xffff0000, v136
	v_lshlrev_b32_e32 v26, 16, v137
	v_and_b32_e32 v27, 0xffff0000, v137
	v_pk_add_f32 v[22:23], v[22:23], v[26:27]
	v_pk_add_f32 v[20:21], v[20:21], v[24:25]
	v_lshlrev_b32_e32 v24, 16, v138
	v_and_b32_e32 v25, 0xffff0000, v138
	v_lshlrev_b32_e32 v26, 16, v139
	v_and_b32_e32 v27, 0xffff0000, v139
	v_pk_add_f32 v[26:27], v[18:19], v[26:27]
	v_pk_add_f32 v[18:19], v[16:17], v[24:25]
	v_cvt_pk_bf16_f32 v16, v20, v21
	v_cvt_pk_bf16_f32 v17, v22, v23
	s_nop 0
	v_cvt_pk_bf16_f32 v18, v18, v19
	v_cvt_pk_bf16_f32 v19, v26, v27
	global_store_dwordx4 v[28:29], v[16:19], off offset:256
	s_nop 1
	s_waitcnt vmcnt(15)
	v_lshlrev_b32_e32 v16, 16, v132
	v_and_b32_e32 v17, 0xffff0000, v132
	v_lshlrev_b32_e32 v18, 16, v133
	v_and_b32_e32 v19, 0xffff0000, v133
	v_pk_add_f32 v[14:15], v[14:15], v[18:19]
	v_pk_add_f32 v[12:13], v[12:13], v[16:17]
	v_lshlrev_b32_e32 v16, 16, v134
	v_and_b32_e32 v17, 0xffff0000, v134
	v_lshlrev_b32_e32 v18, 16, v135
	v_and_b32_e32 v19, 0xffff0000, v135
	v_pk_add_f32 v[18:19], v[10:11], v[18:19]
	v_pk_add_f32 v[10:11], v[8:9], v[16:17]
	v_cvt_pk_bf16_f32 v8, v12, v13
	v_lshl_add_u64 v[12:13], s[28:29], 0, v[186:187]
	v_cvt_pk_bf16_f32 v9, v14, v15
	v_cvt_pk_bf16_f32 v10, v10, v11
	v_cvt_pk_bf16_f32 v11, v18, v19
	v_lshl_add_u64 v[12:13], v[12:13], 0, v[184:185]
	global_store_dwordx4 v[12:13], v[8:11], off
	s_nop 1
	s_waitcnt vmcnt(15)
	v_lshlrev_b32_e32 v8, 16, v128
	v_and_b32_e32 v9, 0xffff0000, v128
	v_lshlrev_b32_e32 v10, 16, v129
	v_and_b32_e32 v11, 0xffff0000, v129
	v_pk_add_f32 v[6:7], v[6:7], v[10:11]
	v_pk_add_f32 v[4:5], v[4:5], v[8:9]
	v_lshlrev_b32_e32 v8, 16, v130
	v_and_b32_e32 v9, 0xffff0000, v130
	v_lshlrev_b32_e32 v10, 16, v131
	v_and_b32_e32 v11, 0xffff0000, v131
	v_pk_add_f32 v[10:11], v[2:3], v[10:11]
	v_pk_add_f32 v[2:3], v[0:1], v[8:9]
	v_cvt_pk_bf16_f32 v0, v4, v5
	v_cvt_pk_bf16_f32 v1, v6, v7
	s_nop 0
	v_cvt_pk_bf16_f32 v2, v2, v3
	v_cvt_pk_bf16_f32 v3, v10, v11
	global_store_dwordx4 v[12:13], v[0:3], off offset:256
	s_cbranch_vccnz .LBB0_1252
	s_andn2_b64 vcc, exec, s[8:9]
	s_cbranch_vccnz .LBB0_1251
	s_barrier
	s_branch .LBB0_1251

; __device__ __forceinline__ unsigned cvt_pk_bf16(float lo, float hi) { unsigned r; asm volatile("v_cvt_pk_bf16_f32 %0, %1, %2" : "=v"(r) : "v"(lo), "v"(hi)); return r; }
;     __device__ __forceinline__ void operator()(const f32x4 (&acc)[2][2][4][2], const Unit& u, int wr, int wc, int fr, int fq) const {
;     ...
;             u32x4 bv[2][4][2];
; #pragma unroll
;             for (int ai = 0; ai < 2; ++ai)
; #pragma unroll
;                 for (int m = 0; m < 4; ++m)
; #pragma unroll
;                     for (int bj = 0; bj < 2; ++bj) bv[ai][m][bj] = *(const u32x4*)(baseb + (size_t)(row0 + ai * HALF + m * 16) * ldc + col0 + bj * HALF);
;             asm volatile("" ::: "memory");
; #pragma unroll
;             for (int ai = 0; ai < 2; ++ai)
; #pragma unroll
;                 for (int m = 0; m < 4; ++m)
; #pragma unroll
;                     for (int bj = 0; bj < 2; ++bj) { const u32x4 b = bv[ai][m][bj];
;                         const f32x4 v0 = acc[ai][bj][m][0] + (f32x4){__builtin_bit_cast(float, b.x << 16), __builtin_bit_cast(float, b.x & 0xffff0000u), __builtin_bit_cast(float, b.y << 16), __builtin_bit_cast(float, b.y & 0xffff0000u)};
;                         const f32x4 v1 = acc[ai][bj][m][1] + (f32x4){__builtin_bit_cast(float, b.z << 16), __builtin_bit_cast(float, b.z & 0xffff0000u), __builtin_bit_cast(float, b.w << 16), __builtin_bit_cast(float, b.w & 0xffff0000u)};
;                         u32x4 w; w.x = cvt_pk_bf16(v0[0], v0[1]); w.y = cvt_pk_bf16(v0[2], v0[3]); w.z = cvt_pk_bf16(v1[0], v1[1]); w.w = cvt_pk_bf16(v1[2], v1[3]);
;                         *(u32x4*)(outb + (size_t)(row0 + ai * HALF + m * 16) * ldc + col0 + bj * HALF) = w; }
.LBB0_1415:
	v_lshl_or_b32 v130, s24, 8, v201
	v_lshl_add_u32 v128, s40, 8, v199
	v_ashrrev_i32_e32 v131, 31, v130
	v_lshlrev_b64 v[184:185], 1, v[130:131]
	v_ashrrev_i32_e32 v129, 31, v128
	v_lshl_add_u64 v[130:131], s[44:45], 0, v[184:185]
	v_lshlrev_b64 v[132:133], 12, v[128:129]
	v_lshl_add_u64 v[134:135], v[130:131], 0, v[132:133]
	global_load_dwordx4 v[206:209], v[134:135], off
	global_load_dwordx4 v[210:213], v[134:135], off offset:256
	v_or_b32_e32 v134, 16, v128
	v_ashrrev_i32_e32 v135, 31, v134
	v_lshlrev_b64 v[230:231], 12, v[134:135]
	v_lshl_add_u64 v[134:135], v[130:131], 0, v[230:231]
	global_load_dwordx4 v[214:217], v[134:135], off
	global_load_dwordx4 v[218:221], v[134:135], off offset:256
	v_or_b32_e32 v136, 32, v128
	v_or_b32_e32 v128, 48, v128
	v_ashrrev_i32_e32 v137, 31, v136
	v_ashrrev_i32_e32 v129, 31, v128
	v_lshlrev_b64 v[196:197], 12, v[136:137]
	v_lshlrev_b64 v[194:195], 12, v[128:129]
	v_lshl_add_u64 v[192:193], v[132:133], 0, s[12:13]
	v_lshl_add_u64 v[190:191], v[132:133], 0, s[14:15]
	v_lshl_add_u64 v[188:189], v[132:133], 0, s[16:17]
	v_lshl_add_u64 v[186:187], v[132:133], 0, s[18:19]
	v_lshl_add_u64 v[128:129], s[36:37], 0, v[132:133]
	v_lshl_add_u64 v[132:133], v[130:131], 0, v[196:197]
	v_lshl_add_u64 v[134:135], v[130:131], 0, v[194:195]
	v_lshl_add_u64 v[136:137], v[130:131], 0, v[192:193]
	v_lshl_add_u64 v[138:139], v[130:131], 0, v[190:191]
	v_lshl_add_u64 v[232:233], v[130:131], 0, v[188:189]
	v_lshl_add_u64 v[130:131], v[130:131], 0, v[186:187]
	v_lshl_add_u64 v[234:235], v[128:129], 0, v[184:185]
	global_load_dwordx4 v[222:225], v[132:133], off
	global_load_dwordx4 v[226:229], v[132:133], off offset:256
	global_load_dwordx4 v[164:167], v[134:135], off
	global_load_dwordx4 v[160:163], v[134:135], off offset:256
	global_load_dwordx4 v[156:159], v[136:137], off
	global_load_dwordx4 v[152:155], v[136:137], off offset:256
	global_load_dwordx4 v[148:151], v[138:139], off
	global_load_dwordx4 v[144:147], v[138:139], off offset:256
	global_load_dwordx4 v[140:143], v[232:233], off
	s_nop 0
	global_load_dwordx4 v[136:139], v[232:233], off offset:256
	global_load_dwordx4 v[132:135], v[130:131], off
	s_nop 0
	global_load_dwordx4 v[128:131], v[130:131], off offset:256
	s_andn2_b64 vcc, exec, s[4:5]
	s_mov_b64 s[4:5], -1
	s_waitcnt vmcnt(15)
	v_lshlrev_b32_e32 v232, 16, v206
	v_and_b32_e32 v233, 0xffff0000, v206
	v_lshlrev_b32_e32 v206, 16, v207
	v_and_b32_e32 v207, 0xffff0000, v207
	v_lshlrev_b32_e32 v236, 16, v208
	v_and_b32_e32 v237, 0xffff0000, v208
	v_lshlrev_b32_e32 v208, 16, v209
	v_and_b32_e32 v209, 0xffff0000, v209
	s_waitcnt vmcnt(14)
	v_lshlrev_b32_e32 v240, 16, v212
	v_and_b32_e32 v241, 0xffff0000, v212
	v_lshlrev_b32_e32 v212, 16, v213
	v_and_b32_e32 v213, 0xffff0000, v213
	v_lshlrev_b32_e32 v238, 16, v210
	v_and_b32_e32 v239, 0xffff0000, v210
	v_lshlrev_b32_e32 v210, 16, v211
	v_and_b32_e32 v211, 0xffff0000, v211
	v_pk_add_f32 v[126:127], v[126:127], v[206:207]
	v_pk_add_f32 v[124:125], v[124:125], v[232:233]
	v_pk_add_f32 v[122:123], v[122:123], v[208:209]
	v_pk_add_f32 v[120:121], v[120:121], v[236:237]
	v_pk_add_f32 v[206:207], v[106:107], v[212:213]
	v_pk_add_f32 v[208:209], v[104:105], v[240:241]
	v_cvt_pk_bf16_f32 v104, v124, v125
	v_cvt_pk_bf16_f32 v105, v126, v127
	v_cvt_pk_bf16_f32 v106, v120, v121
	v_cvt_pk_bf16_f32 v107, v122, v123
	s_waitcnt vmcnt(13)
	v_lshlrev_b32_e32 v244, 16, v216
	v_and_b32_e32 v245, 0xffff0000, v216
	v_pk_add_f32 v[114:115], v[114:115], v[210:211]
	v_pk_add_f32 v[112:113], v[112:113], v[238:239]
	global_store_dwordx4 v[234:235], v[104:107], off
	v_lshlrev_b32_e32 v242, 16, v214
	v_and_b32_e32 v243, 0xffff0000, v214
	v_cvt_pk_bf16_f32 v104, v112, v113
	v_cvt_pk_bf16_f32 v105, v114, v115
	v_cvt_pk_bf16_f32 v106, v208, v209
	v_cvt_pk_bf16_f32 v107, v206, v207
	v_lshlrev_b32_e32 v214, 16, v215
	v_and_b32_e32 v215, 0xffff0000, v215
	v_lshlrev_b32_e32 v216, 16, v217
	global_store_dwordx4 v[234:235], v[104:107], off offset:256
	v_and_b32_e32 v217, 0xffff0000, v217
	v_pk_add_f32 v[118:119], v[118:119], v[214:215]
	v_pk_add_f32 v[106:107], v[108:109], v[244:245]
	v_lshl_add_u64 v[108:109], s[36:37], 0, v[230:231]
	v_pk_add_f32 v[116:117], v[116:117], v[242:243]
	v_pk_add_f32 v[110:111], v[110:111], v[216:217]
	v_cvt_pk_bf16_f32 v104, v116, v117
	v_cvt_pk_bf16_f32 v105, v118, v119
	v_cvt_pk_bf16_f32 v106, v106, v107
	v_lshl_add_u64 v[108:109], v[108:109], 0, v[184:185]
	v_cvt_pk_bf16_f32 v107, v110, v111
	global_store_dwordx4 v[108:109], v[104:107], off
	s_nop 1
	s_waitcnt vmcnt(15)
	v_lshlrev_b32_e32 v104, 16, v218
	v_and_b32_e32 v105, 0xffff0000, v218
	v_lshlrev_b32_e32 v106, 16, v219
	v_and_b32_e32 v107, 0xffff0000, v219
	v_pk_add_f32 v[102:103], v[102:103], v[106:107]
	v_pk_add_f32 v[100:101], v[100:101], v[104:105]
	v_lshlrev_b32_e32 v104, 16, v220
	v_and_b32_e32 v105, 0xffff0000, v220
	v_lshlrev_b32_e32 v106, 16, v221
	v_and_b32_e32 v107, 0xffff0000, v221
	v_pk_add_f32 v[106:107], v[98:99], v[106:107]
	v_pk_add_f32 v[98:99], v[96:97], v[104:105]
	v_cvt_pk_bf16_f32 v96, v100, v101
	v_cvt_pk_bf16_f32 v97, v102, v103
	s_nop 0
	v_cvt_pk_bf16_f32 v98, v98, v99
	v_cvt_pk_bf16_f32 v99, v106, v107
	global_store_dwordx4 v[108:109], v[96:99], off offset:256
	s_nop 1
	s_waitcnt vmcnt(15)
	v_lshlrev_b32_e32 v96, 16, v222
	v_and_b32_e32 v97, 0xffff0000, v222
	v_lshlrev_b32_e32 v98, 16, v223
	v_and_b32_e32 v99, 0xffff0000, v223
	v_pk_add_f32 v[94:95], v[94:95], v[98:99]
	v_pk_add_f32 v[92:93], v[92:93], v[96:97]
	v_lshlrev_b32_e32 v96, 16, v224
	v_and_b32_e32 v97, 0xffff0000, v224
	v_lshlrev_b32_e32 v98, 16, v225
	v_and_b32_e32 v99, 0xffff0000, v225
	v_pk_add_f32 v[98:99], v[90:91], v[98:99]
	v_pk_add_f32 v[90:91], v[88:89], v[96:97]
	v_cvt_pk_bf16_f32 v88, v92, v93
	v_lshl_add_u64 v[92:93], s[36:37], 0, v[196:197]
	v_cvt_pk_bf16_f32 v89, v94, v95
	v_cvt_pk_bf16_f32 v90, v90, v91
	v_cvt_pk_bf16_f32 v91, v98, v99
	v_lshl_add_u64 v[92:93], v[92:93], 0, v[184:185]
	global_store_dwordx4 v[92:93], v[88:91], off
	s_nop 1
	s_waitcnt vmcnt(15)
; __device__ __forceinline__ unsigned cvt_pk_bf16(float lo, float hi) { unsigned r; asm volatile("v_cvt_pk_bf16_f32 %0, %1, %2" : "=v"(r) : "v"(lo), "v"(hi)); return r; }
;     __device__ __forceinline__ void operator()(const f32x4 (&acc)[2][2][4][2], const Unit& u, int wr, int wc, int fr, int fq) const {
;     ...
; #pragma unroll
;             for (int ai = 0; ai < 2; ++ai)
; #pragma unroll
;                 for (int m = 0; m < 4; ++m)
; #pragma unroll
;                     for (int bj = 0; bj < 2; ++bj) { const u32x4 b = bv[ai][m][bj];
;                         const f32x4 v0 = acc[ai][bj][m][0] + (f32x4){__builtin_bit_cast(float, b.x << 16), __builtin_bit_cast(float, b.x & 0xffff0000u), __builtin_bit_cast(float, b.y << 16), __builtin_bit_cast(float, b.y & 0xffff0000u)};
;                         const f32x4 v1 = acc[ai][bj][m][1] + (f32x4){__builtin_bit_cast(float, b.z << 16), __builtin_bit_cast(float, b.z & 0xffff0000u), __builtin_bit_cast(float, b.w << 16), __builtin_bit_cast(float, b.w & 0xffff0000u)};
;                         u32x4 w; w.x = cvt_pk_bf16(v0[0], v0[1]); w.y = cvt_pk_bf16(v0[2], v0[3]); w.z = cvt_pk_bf16(v1[0], v1[1]); w.w = cvt_pk_bf16(v1[2], v1[3]);
;                         *(u32x4*)(outb + (size_t)(row0 + ai * HALF + m * 16) * ldc + col0 + bj * HALF) = w; }
	v_lshlrev_b32_e32 v88, 16, v226
	v_and_b32_e32 v89, 0xffff0000, v226
	v_lshlrev_b32_e32 v90, 16, v227
	v_and_b32_e32 v91, 0xffff0000, v227
	v_pk_add_f32 v[86:87], v[86:87], v[90:91]
	v_pk_add_f32 v[84:85], v[84:85], v[88:89]
	v_lshlrev_b32_e32 v88, 16, v228
	v_and_b32_e32 v89, 0xffff0000, v228
	v_lshlrev_b32_e32 v90, 16, v229
	v_and_b32_e32 v91, 0xffff0000, v229
	v_pk_add_f32 v[90:91], v[82:83], v[90:91]
	v_pk_add_f32 v[82:83], v[80:81], v[88:89]
	v_cvt_pk_bf16_f32 v80, v84, v85
	v_cvt_pk_bf16_f32 v81, v86, v87
	s_nop 0
	v_cvt_pk_bf16_f32 v82, v82, v83
	v_cvt_pk_bf16_f32 v83, v90, v91
	global_store_dwordx4 v[92:93], v[80:83], off offset:256
	s_nop 1
	s_waitcnt vmcnt(15)
	v_lshlrev_b32_e32 v80, 16, v164
	v_and_b32_e32 v81, 0xffff0000, v164
	v_lshlrev_b32_e32 v82, 16, v165
	v_and_b32_e32 v83, 0xffff0000, v165
	v_pk_add_f32 v[78:79], v[78:79], v[82:83]
	v_pk_add_f32 v[76:77], v[76:77], v[80:81]
	v_lshlrev_b32_e32 v80, 16, v166
	v_and_b32_e32 v81, 0xffff0000, v166
	v_lshlrev_b32_e32 v82, 16, v167
	v_and_b32_e32 v83, 0xffff0000, v167
	v_pk_add_f32 v[82:83], v[74:75], v[82:83]
	v_pk_add_f32 v[74:75], v[72:73], v[80:81]
	v_cvt_pk_bf16_f32 v72, v76, v77
	v_lshl_add_u64 v[76:77], s[36:37], 0, v[194:195]
	v_cvt_pk_bf16_f32 v73, v78, v79
	v_cvt_pk_bf16_f32 v74, v74, v75
	v_cvt_pk_bf16_f32 v75, v82, v83
	v_lshl_add_u64 v[76:77], v[76:77], 0, v[184:185]
	global_store_dwordx4 v[76:77], v[72:75], off
	s_nop 1
	s_waitcnt vmcnt(15)
	v_lshlrev_b32_e32 v72, 16, v160
	v_and_b32_e32 v73, 0xffff0000, v160
	v_lshlrev_b32_e32 v74, 16, v161
	v_and_b32_e32 v75, 0xffff0000, v161
	v_pk_add_f32 v[70:71], v[70:71], v[74:75]
	v_pk_add_f32 v[68:69], v[68:69], v[72:73]
	v_lshlrev_b32_e32 v72, 16, v162
	v_and_b32_e32 v73, 0xffff0000, v162
	v_lshlrev_b32_e32 v74, 16, v163
	v_and_b32_e32 v75, 0xffff0000, v163
	v_pk_add_f32 v[74:75], v[66:67], v[74:75]
	v_pk_add_f32 v[66:67], v[64:65], v[72:73]
	v_cvt_pk_bf16_f32 v64, v68, v69
	v_cvt_pk_bf16_f32 v65, v70, v71
	s_nop 0
	v_cvt_pk_bf16_f32 v66, v66, v67
	v_cvt_pk_bf16_f32 v67, v74, v75
	global_store_dwordx4 v[76:77], v[64:67], off offset:256
	s_nop 1
	s_waitcnt vmcnt(15)
	v_lshlrev_b32_e32 v64, 16, v156
	v_and_b32_e32 v65, 0xffff0000, v156
	v_lshlrev_b32_e32 v66, 16, v157
	v_and_b32_e32 v67, 0xffff0000, v157
	v_pk_add_f32 v[62:63], v[62:63], v[66:67]
	v_pk_add_f32 v[60:61], v[60:61], v[64:65]
	v_lshlrev_b32_e32 v64, 16, v158
	v_and_b32_e32 v65, 0xffff0000, v158
	v_lshlrev_b32_e32 v66, 16, v159
	v_and_b32_e32 v67, 0xffff0000, v159
	v_pk_add_f32 v[66:67], v[58:59], v[66:67]
	v_pk_add_f32 v[58:59], v[56:57], v[64:65]
	v_cvt_pk_bf16_f32 v56, v60, v61
	v_lshl_add_u64 v[60:61], s[36:37], 0, v[192:193]
	v_cvt_pk_bf16_f32 v57, v62, v63
	v_cvt_pk_bf16_f32 v58, v58, v59
	v_cvt_pk_bf16_f32 v59, v66, v67
	v_lshl_add_u64 v[60:61], v[60:61], 0, v[184:185]
	global_store_dwordx4 v[60:61], v[56:59], off
	s_nop 1
	s_waitcnt vmcnt(15)
	v_lshlrev_b32_e32 v56, 16, v152
	v_and_b32_e32 v57, 0xffff0000, v152
	v_lshlrev_b32_e32 v58, 16, v153
	v_and_b32_e32 v59, 0xffff0000, v153
	v_pk_add_f32 v[54:55], v[54:55], v[58:59]
	v_pk_add_f32 v[52:53], v[52:53], v[56:57]
	v_lshlrev_b32_e32 v56, 16, v154
	v_and_b32_e32 v57, 0xffff0000, v154
	v_lshlrev_b32_e32 v58, 16, v155
	v_and_b32_e32 v59, 0xffff0000, v155
	v_pk_add_f32 v[58:59], v[50:51], v[58:59]
	v_pk_add_f32 v[50:51], v[48:49], v[56:57]
	v_cvt_pk_bf16_f32 v48, v52, v53
	v_cvt_pk_bf16_f32 v49, v54, v55
	s_nop 0
	v_cvt_pk_bf16_f32 v50, v50, v51
	v_cvt_pk_bf16_f32 v51, v58, v59
	global_store_dwordx4 v[60:61], v[48:51], off offset:256
	s_nop 1
	s_waitcnt vmcnt(15)
	v_lshlrev_b32_e32 v48, 16, v148
	v_and_b32_e32 v49, 0xffff0000, v148
	v_lshlrev_b32_e32 v50, 16, v149
	v_and_b32_e32 v51, 0xffff0000, v149
	v_pk_add_f32 v[46:47], v[46:47], v[50:51]
	v_pk_add_f32 v[44:45], v[44:45], v[48:49]
	v_lshlrev_b32_e32 v48, 16, v150
	v_and_b32_e32 v49, 0xffff0000, v150
	v_lshlrev_b32_e32 v50, 16, v151
	v_and_b32_e32 v51, 0xffff0000, v151
	v_pk_add_f32 v[50:51], v[42:43], v[50:51]
	v_pk_add_f32 v[42:43], v[40:41], v[48:49]
	v_cvt_pk_bf16_f32 v40, v44, v45
	v_lshl_add_u64 v[44:45], s[36:37], 0, v[190:191]
	v_cvt_pk_bf16_f32 v41, v46, v47
	v_cvt_pk_bf16_f32 v42, v42, v43
	v_cvt_pk_bf16_f32 v43, v50, v51
	v_lshl_add_u64 v[44:45], v[44:45], 0, v[184:185]
	global_store_dwordx4 v[44:45], v[40:43], off
	s_nop 1
	s_waitcnt vmcnt(15)
; __device__ __forceinline__ unsigned cvt_pk_bf16(float lo, float hi) { unsigned r; asm volatile("v_cvt_pk_bf16_f32 %0, %1, %2" : "=v"(r) : "v"(lo), "v"(hi)); return r; }
;     __device__ __forceinline__ void operator()(const f32x4 (&acc)[2][2][4][2], const Unit& u, int wr, int wc, int fr, int fq) const {
;     ...
; #pragma unroll
;             for (int ai = 0; ai < 2; ++ai)
; #pragma unroll
;                 for (int m = 0; m < 4; ++m)
; #pragma unroll
;                     for (int bj = 0; bj < 2; ++bj) { const u32x4 b = bv[ai][m][bj];
;                         const f32x4 v0 = acc[ai][bj][m][0] + (f32x4){__builtin_bit_cast(float, b.x << 16), __builtin_bit_cast(float, b.x & 0xffff0000u), __builtin_bit_cast(float, b.y << 16), __builtin_bit_cast(float, b.y & 0xffff0000u)};
;                         const f32x4 v1 = acc[ai][bj][m][1] + (f32x4){__builtin_bit_cast(float, b.z << 16), __builtin_bit_cast(float, b.z & 0xffff0000u), __builtin_bit_cast(float, b.w << 16), __builtin_bit_cast(float, b.w & 0xffff0000u)};
;                         u32x4 w; w.x = cvt_pk_bf16(v0[0], v0[1]); w.y = cvt_pk_bf16(v0[2], v0[3]); w.z = cvt_pk_bf16(v1[0], v1[1]); w.w = cvt_pk_bf16(v1[2], v1[3]);
;                         *(u32x4*)(outb + (size_t)(row0 + ai * HALF + m * 16) * ldc + col0 + bj * HALF) = w; }
	v_lshlrev_b32_e32 v40, 16, v144
	v_and_b32_e32 v41, 0xffff0000, v144
	v_lshlrev_b32_e32 v42, 16, v145
	v_and_b32_e32 v43, 0xffff0000, v145
	v_pk_add_f32 v[38:39], v[38:39], v[42:43]
	v_pk_add_f32 v[36:37], v[36:37], v[40:41]
	v_lshlrev_b32_e32 v40, 16, v146
	v_and_b32_e32 v41, 0xffff0000, v146
	v_lshlrev_b32_e32 v42, 16, v147
	v_and_b32_e32 v43, 0xffff0000, v147
	v_pk_add_f32 v[42:43], v[34:35], v[42:43]
	v_pk_add_f32 v[34:35], v[32:33], v[40:41]
	v_cvt_pk_bf16_f32 v32, v36, v37
	v_cvt_pk_bf16_f32 v33, v38, v39
	s_nop 0
	v_cvt_pk_bf16_f32 v34, v34, v35
	v_cvt_pk_bf16_f32 v35, v42, v43
	global_store_dwordx4 v[44:45], v[32:35], off offset:256
	s_nop 1
	s_waitcnt vmcnt(15)
	v_lshlrev_b32_e32 v32, 16, v140
	v_and_b32_e32 v33, 0xffff0000, v140
	v_lshlrev_b32_e32 v34, 16, v141
	v_and_b32_e32 v35, 0xffff0000, v141
	v_pk_add_f32 v[30:31], v[30:31], v[34:35]
	v_pk_add_f32 v[28:29], v[28:29], v[32:33]
	v_lshlrev_b32_e32 v32, 16, v142
	v_and_b32_e32 v33, 0xffff0000, v142
	v_lshlrev_b32_e32 v34, 16, v143
	v_and_b32_e32 v35, 0xffff0000, v143
	v_pk_add_f32 v[34:35], v[26:27], v[34:35]
	v_pk_add_f32 v[26:27], v[24:25], v[32:33]
	v_cvt_pk_bf16_f32 v24, v28, v29
	v_lshl_add_u64 v[28:29], s[36:37], 0, v[188:189]
	v_cvt_pk_bf16_f32 v25, v30, v31
	v_cvt_pk_bf16_f32 v26, v26, v27
	v_cvt_pk_bf16_f32 v27, v34, v35
	v_lshl_add_u64 v[28:29], v[28:29], 0, v[184:185]
	global_store_dwordx4 v[28:29], v[24:27], off
	s_nop 1
	s_waitcnt vmcnt(15)
	v_lshlrev_b32_e32 v24, 16, v136
	v_and_b32_e32 v25, 0xffff0000, v136
	v_lshlrev_b32_e32 v26, 16, v137
	v_and_b32_e32 v27, 0xffff0000, v137
	v_pk_add_f32 v[22:23], v[22:23], v[26:27]
	v_pk_add_f32 v[20:21], v[20:21], v[24:25]
	v_lshlrev_b32_e32 v24, 16, v138
	v_and_b32_e32 v25, 0xffff0000, v138
	v_lshlrev_b32_e32 v26, 16, v139
	v_and_b32_e32 v27, 0xffff0000, v139
	v_pk_add_f32 v[26:27], v[18:19], v[26:27]
	v_pk_add_f32 v[18:19], v[16:17], v[24:25]
	v_cvt_pk_bf16_f32 v16, v20, v21
	v_cvt_pk_bf16_f32 v17, v22, v23
	s_nop 0
	v_cvt_pk_bf16_f32 v18, v18, v19
	v_cvt_pk_bf16_f32 v19, v26, v27
	global_store_dwordx4 v[28:29], v[16:19], off offset:256
	s_nop 1
	s_waitcnt vmcnt(15)
	v_lshlrev_b32_e32 v16, 16, v132
	v_and_b32_e32 v17, 0xffff0000, v132
	v_lshlrev_b32_e32 v18, 16, v133
	v_and_b32_e32 v19, 0xffff0000, v133
	v_pk_add_f32 v[14:15], v[14:15], v[18:19]
	v_pk_add_f32 v[12:13], v[12:13], v[16:17]
	v_lshlrev_b32_e32 v16, 16, v134
	v_and_b32_e32 v17, 0xffff0000, v134
	v_lshlrev_b32_e32 v18, 16, v135
	v_and_b32_e32 v19, 0xffff0000, v135
	v_pk_add_f32 v[18:19], v[10:11], v[18:19]
	v_pk_add_f32 v[10:11], v[8:9], v[16:17]
	v_cvt_pk_bf16_f32 v8, v12, v13
	v_lshl_add_u64 v[12:13], s[36:37], 0, v[186:187]
	v_cvt_pk_bf16_f32 v9, v14, v15
	v_cvt_pk_bf16_f32 v10, v10, v11
	v_cvt_pk_bf16_f32 v11, v18, v19
	v_lshl_add_u64 v[12:13], v[12:13], 0, v[184:185]
	global_store_dwordx4 v[12:13], v[8:11], off
	s_nop 1
	s_waitcnt vmcnt(15)
	v_lshlrev_b32_e32 v8, 16, v128
	v_and_b32_e32 v9, 0xffff0000, v128
	v_lshlrev_b32_e32 v10, 16, v129
	v_and_b32_e32 v11, 0xffff0000, v129
	v_pk_add_f32 v[6:7], v[6:7], v[10:11]
	v_pk_add_f32 v[4:5], v[4:5], v[8:9]
	v_lshlrev_b32_e32 v8, 16, v130
	v_and_b32_e32 v9, 0xffff0000, v130
	v_lshlrev_b32_e32 v10, 16, v131
	v_and_b32_e32 v11, 0xffff0000, v131
	v_pk_add_f32 v[10:11], v[2:3], v[10:11]
	v_pk_add_f32 v[2:3], v[0:1], v[8:9]
	v_cvt_pk_bf16_f32 v0, v4, v5
	v_cvt_pk_bf16_f32 v1, v6, v7
	s_nop 0
	v_cvt_pk_bf16_f32 v2, v2, v3
	v_cvt_pk_bf16_f32 v3, v10, v11
	global_store_dwordx4 v[12:13], v[0:3], off offset:256
	s_cbranch_vccnz .LBB0_1404
	s_andn2_b64 vcc, exec, s[6:7]
	s_cbranch_vccnz .LBB0_1403
	s_barrier
	s_branch .LBB0_1403
